# EpiMerge of fnet-out / w_o / s5-out GEMMs: f32 accumulators staged through LDS (XOR-swizzled, two 128-row passes) so gate/merged bf16 tiles are read and written with full-row coalesced accesses
# speedup vs baseline: 1.0041x; 1.0041x over previous
; #define EPI_FOR(u) \
;     _Pragma("unroll") for (int ai = 0; ai < 2; ++ai) _Pragma("unroll") for (int m = 0; m < 4; ++m) _Pragma("unroll") for (int bj = 0; bj < 2; ++bj)
; #define EPI_COL(u) (EPI_CB(u) + 8 * fq)
; DI u32x4 pack8(const float* v) { u32x4 w; w.x = pk2(v[0], v[1]); w.y = pk2(v[2], v[3]); w.z = pk2(v[4], v[5]); w.w = pk2(v[6], v[7]); return w; }
;     DI void operator()(const Acc& acc, const Unit& u, int wr, int wc, int fr, int fq) const {
;         EPI_FOR(u) {
;             const int row = EPI_ROW(u), col = EPI_COL(u); EPI_V(v);
;             const u32x4 gg = *(const u32x4*)(gate + (size_t)row * 3072 + gi * 1024 + col);
;             const float gf[8] = {bflo(gg.x), bfhi(gg.x), bflo(gg.y), bfhi(gg.y), bflo(gg.z), bfhi(gg.z), bflo(gg.w), bfhi(gg.w)};
;             bf16_t* mp = mrg + (size_t)row * 1024 + col;
;             if (accum) {
;                 const u32x4 oo = *(const u32x4*)mp;
;                 const float of[8] = {bflo(oo.x), bfhi(oo.x), bflo(oo.y), bfhi(oo.y), bflo(oo.z), bfhi(oo.z), bflo(oo.w), bfhi(oo.w)};
; #pragma unroll
;                 for (int j = 0; j < 8; ++j) v[j] = of[j] + gf[j] * v[j];
;             } else {
; #pragma unroll
;                 for (int j = 0; j < 8; ++j) v[j] = gf[j] * v[j];
;             }
;             *(u32x4*)mp = pack8(v);
.LBB0_1061:
	s_lshl_b32 s2, s28, 8
	s_lshl_b32 s6, s29, 8
	v_readfirstlane_b32 s7, v232
	s_lshr_b32 s7, s7, 6
	s_lshl_b32 s7, s7, 4
	v_add_u32_e32 v210, s51, v145
	v_lshlrev_b32_e32 v210, 10, v210
	v_and_b32_e32 v211, 7, v145
	v_lshlrev_b32_e32 v212, 1, v144
	v_xor_b32_e32 v211, v212, v211
	v_lshl_add_u32 v210, v211, 4, v210
	s_lshl_b32 s8, s54, 2
	v_add_u32_e32 v210, s8, v210
	v_xor_b32_e32 v211, 16, v210
	v_lshrrev_b32_e32 v212, 5, v233
	v_and_b32_e32 v213, 31, v233
	v_lshl_add_u32 v214, v213, 3, s6
	v_lshlrev_b32_e32 v214, 1, v214
	v_lshlrev_b32_e32 v213, 1, v213
	s_waitcnt vmcnt(0)
	s_barrier
	ds_write_b128 v210, v[124:127]
	ds_write_b128 v211, v[120:123]
	ds_write_b128 v210, v[116:119] offset:512
	ds_write_b128 v211, v[112:115] offset:512
	ds_write_b128 v210, v[108:111] offset:16384
	ds_write_b128 v211, v[104:107] offset:16384
	ds_write_b128 v210, v[100:103] offset:16896
	ds_write_b128 v211, v[96:99] offset:16896
	ds_write_b128 v210, v[92:95] offset:32768
	ds_write_b128 v211, v[88:91] offset:32768
	ds_write_b128 v210, v[84:87] offset:33280
	ds_write_b128 v211, v[80:83] offset:33280
	ds_write_b128 v210, v[76:79] offset:49152
	ds_write_b128 v211, v[72:75] offset:49152
	ds_write_b128 v210, v[68:71] offset:49664
	ds_write_b128 v211, v[64:67] offset:49664
	s_waitcnt lgkmcnt(0)
	s_barrier
	v_add_u32_e32 v215, s7, v212
	s_add_i32 s8, s2, 0
	v_add_u32_e32 v216, s8, v215
	v_mul_u32_u24_e32 v217, 0x1800, v216
	v_add_u32_e32 v217, v217, v214
	v_add_u32_e32 v217, 0x0, v217
	v_lshl_add_u32 v218, v216, 11, v214
	global_load_dwordx4 v[128:131], v217, s[22:23]
	v_add_u32_e32 v219, 0x3000, v217
	global_load_dwordx4 v[132:135], v219, s[22:23]
	v_add_u32_e32 v219, 0x6000, v217
	global_load_dwordx4 v[136:139], v219, s[22:23]
	v_add_u32_e32 v219, 0x9000, v217
	global_load_dwordx4 v[140:143], v219, s[22:23]
	v_add_u32_e32 v219, 0xc000, v217
	global_load_dwordx4 v[144:147], v219, s[22:23]
	v_add_u32_e32 v219, 0xf000, v217
	global_load_dwordx4 v[148:151], v219, s[22:23]
	v_add_u32_e32 v219, 0x12000, v217
	global_load_dwordx4 v[152:155], v219, s[22:23]
	v_add_u32_e32 v219, 0x15000, v217
	global_load_dwordx4 v[156:159], v219, s[22:23]
	v_add_u32_e32 v219, 0, v212
	v_and_b32_e32 v219, 7, v219
	v_xor_b32_e32 v219, v213, v219
	v_add_u32_e32 v228, 0, v215
	v_lshlrev_b32_e32 v228, 10, v228
	v_lshl_add_u32 v228, v219, 4, v228
	v_xor_b32_e32 v229, 16, v228
	ds_read_b128 v[244:247], v228
	ds_read_b128 v[220:223], v229
	s_waitcnt vmcnt(7)
	s_waitcnt lgkmcnt(0)
	v_lshlrev_b32_e32 v184, 16, v128
	v_and_b32_e32 v185, 0xffff0000, v128
	v_pk_mul_f32 v[244:245], v[244:245], v[184:185]
	v_lshlrev_b32_e32 v184, 16, v129
	v_and_b32_e32 v185, 0xffff0000, v129
	v_pk_mul_f32 v[246:247], v[246:247], v[184:185]
	v_lshlrev_b32_e32 v184, 16, v130
	v_and_b32_e32 v185, 0xffff0000, v130
	v_pk_mul_f32 v[220:221], v[220:221], v[184:185]
	v_lshlrev_b32_e32 v184, 16, v131
	v_and_b32_e32 v185, 0xffff0000, v131
	v_pk_mul_f32 v[222:223], v[222:223], v[184:185]
	v_cvt_pk_bf16_f32 v128, v244, v245
	v_cvt_pk_bf16_f32 v129, v246, v247
	v_cvt_pk_bf16_f32 v130, v220, v221
	v_cvt_pk_bf16_f32 v131, v222, v223
	global_store_dwordx4 v218, v[128:131], s[24:25]
	v_add_u32_e32 v219, 2, v212
	v_and_b32_e32 v219, 7, v219
	v_xor_b32_e32 v219, v213, v219
	v_add_u32_e32 v228, 2, v215
	v_lshlrev_b32_e32 v228, 10, v228
	v_lshl_add_u32 v228, v219, 4, v228
	v_xor_b32_e32 v229, 16, v228
	ds_read_b128 v[244:247], v228
	ds_read_b128 v[220:223], v229
	s_waitcnt vmcnt(7)
	s_waitcnt lgkmcnt(0)
	v_lshlrev_b32_e32 v184, 16, v132
	v_and_b32_e32 v185, 0xffff0000, v132
	v_pk_mul_f32 v[244:245], v[244:245], v[184:185]
	v_lshlrev_b32_e32 v184, 16, v133
	v_and_b32_e32 v185, 0xffff0000, v133
	v_pk_mul_f32 v[246:247], v[246:247], v[184:185]
	v_lshlrev_b32_e32 v184, 16, v134
	v_and_b32_e32 v185, 0xffff0000, v134
	v_pk_mul_f32 v[220:221], v[220:221], v[184:185]
	v_lshlrev_b32_e32 v184, 16, v135
	v_and_b32_e32 v185, 0xffff0000, v135
	v_pk_mul_f32 v[222:223], v[222:223], v[184:185]
	v_cvt_pk_bf16_f32 v132, v244, v245
	v_cvt_pk_bf16_f32 v133, v246, v247
	v_cvt_pk_bf16_f32 v134, v220, v221
	v_cvt_pk_bf16_f32 v135, v222, v223
	v_add_u32_e32 v219, 0x1000, v218
	global_store_dwordx4 v219, v[132:135], s[24:25]
	v_add_u32_e32 v219, 4, v212
	v_and_b32_e32 v219, 7, v219
	v_xor_b32_e32 v219, v213, v219
	v_add_u32_e32 v228, 4, v215
	v_lshlrev_b32_e32 v228, 10, v228
	v_lshl_add_u32 v228, v219, 4, v228
	v_xor_b32_e32 v229, 16, v228
	ds_read_b128 v[244:247], v228
	ds_read_b128 v[220:223], v229
	s_waitcnt vmcnt(7)
	s_waitcnt lgkmcnt(0)
	v_lshlrev_b32_e32 v184, 16, v136
	v_and_b32_e32 v185, 0xffff0000, v136
	v_pk_mul_f32 v[244:245], v[244:245], v[184:185]
	v_lshlrev_b32_e32 v184, 16, v137
	v_and_b32_e32 v185, 0xffff0000, v137
	v_pk_mul_f32 v[246:247], v[246:247], v[184:185]
	v_lshlrev_b32_e32 v184, 16, v138
	v_and_b32_e32 v185, 0xffff0000, v138
	v_pk_mul_f32 v[220:221], v[220:221], v[184:185]
	v_lshlrev_b32_e32 v184, 16, v139
	v_and_b32_e32 v185, 0xffff0000, v139
	v_pk_mul_f32 v[222:223], v[222:223], v[184:185]
	v_cvt_pk_bf16_f32 v136, v244, v245
	v_cvt_pk_bf16_f32 v137, v246, v247
	v_cvt_pk_bf16_f32 v138, v220, v221
	v_cvt_pk_bf16_f32 v139, v222, v223
	v_add_u32_e32 v219, 0x2000, v218
	global_store_dwordx4 v219, v[136:139], s[24:25]
	v_add_u32_e32 v219, 6, v212
	v_and_b32_e32 v219, 7, v219
	v_xor_b32_e32 v219, v213, v219
	v_add_u32_e32 v228, 6, v215
	v_lshlrev_b32_e32 v228, 10, v228
	v_lshl_add_u32 v228, v219, 4, v228
	v_xor_b32_e32 v229, 16, v228
	ds_read_b128 v[244:247], v228
	ds_read_b128 v[220:223], v229
	s_waitcnt vmcnt(7)
	s_waitcnt lgkmcnt(0)
; #define EPI_COL(u) (EPI_CB(u) + 8 * fq)
; DI u32x4 pack8(const float* v) { u32x4 w; w.x = pk2(v[0], v[1]); w.y = pk2(v[2], v[3]); w.z = pk2(v[4], v[5]); w.w = pk2(v[6], v[7]); return w; }
;     DI void operator()(const Acc& acc, const Unit& u, int wr, int wc, int fr, int fq) const {
;     ...
;             const int row = EPI_ROW(u), col = EPI_COL(u); EPI_V(v);
;             const u32x4 gg = *(const u32x4*)(gate + (size_t)row * 3072 + gi * 1024 + col);
;             const float gf[8] = {bflo(gg.x), bfhi(gg.x), bflo(gg.y), bfhi(gg.y), bflo(gg.z), bfhi(gg.z), bflo(gg.w), bfhi(gg.w)};
;             bf16_t* mp = mrg + (size_t)row * 1024 + col;
;             if (accum) {
;                 const u32x4 oo = *(const u32x4*)mp;
;                 const float of[8] = {bflo(oo.x), bfhi(oo.x), bflo(oo.y), bfhi(oo.y), bflo(oo.z), bfhi(oo.z), bflo(oo.w), bfhi(oo.w)};
; #pragma unroll
;                 for (int j = 0; j < 8; ++j) v[j] = of[j] + gf[j] * v[j];
;             } else {
; #pragma unroll
;                 for (int j = 0; j < 8; ++j) v[j] = gf[j] * v[j];
;             }
;             *(u32x4*)mp = pack8(v);
	v_lshlrev_b32_e32 v184, 16, v140
	v_and_b32_e32 v185, 0xffff0000, v140
	v_pk_mul_f32 v[244:245], v[244:245], v[184:185]
	v_lshlrev_b32_e32 v184, 16, v141
	v_and_b32_e32 v185, 0xffff0000, v141
	v_pk_mul_f32 v[246:247], v[246:247], v[184:185]
	v_lshlrev_b32_e32 v184, 16, v142
	v_and_b32_e32 v185, 0xffff0000, v142
	v_pk_mul_f32 v[220:221], v[220:221], v[184:185]
	v_lshlrev_b32_e32 v184, 16, v143
	v_and_b32_e32 v185, 0xffff0000, v143
	v_pk_mul_f32 v[222:223], v[222:223], v[184:185]
	v_cvt_pk_bf16_f32 v140, v244, v245
	v_cvt_pk_bf16_f32 v141, v246, v247
	v_cvt_pk_bf16_f32 v142, v220, v221
	v_cvt_pk_bf16_f32 v143, v222, v223
	v_add_u32_e32 v219, 0x3000, v218
	global_store_dwordx4 v219, v[140:143], s[24:25]
	v_add_u32_e32 v219, 8, v212
	v_and_b32_e32 v219, 7, v219
	v_xor_b32_e32 v219, v213, v219
	v_add_u32_e32 v228, 8, v215
	v_lshlrev_b32_e32 v228, 10, v228
	v_lshl_add_u32 v228, v219, 4, v228
	v_xor_b32_e32 v229, 16, v228
	ds_read_b128 v[244:247], v228
	ds_read_b128 v[220:223], v229
	s_waitcnt vmcnt(7)
	s_waitcnt lgkmcnt(0)
	v_lshlrev_b32_e32 v184, 16, v144
	v_and_b32_e32 v185, 0xffff0000, v144
	v_pk_mul_f32 v[244:245], v[244:245], v[184:185]
	v_lshlrev_b32_e32 v184, 16, v145
	v_and_b32_e32 v185, 0xffff0000, v145
	v_pk_mul_f32 v[246:247], v[246:247], v[184:185]
	v_lshlrev_b32_e32 v184, 16, v146
	v_and_b32_e32 v185, 0xffff0000, v146
	v_pk_mul_f32 v[220:221], v[220:221], v[184:185]
	v_lshlrev_b32_e32 v184, 16, v147
	v_and_b32_e32 v185, 0xffff0000, v147
	v_pk_mul_f32 v[222:223], v[222:223], v[184:185]
	v_cvt_pk_bf16_f32 v144, v244, v245
	v_cvt_pk_bf16_f32 v145, v246, v247
	v_cvt_pk_bf16_f32 v146, v220, v221
	v_cvt_pk_bf16_f32 v147, v222, v223
	v_add_u32_e32 v219, 0x4000, v218
	global_store_dwordx4 v219, v[144:147], s[24:25]
	v_add_u32_e32 v219, 10, v212
	v_and_b32_e32 v219, 7, v219
	v_xor_b32_e32 v219, v213, v219
	v_add_u32_e32 v228, 10, v215
	v_lshlrev_b32_e32 v228, 10, v228
	v_lshl_add_u32 v228, v219, 4, v228
	v_xor_b32_e32 v229, 16, v228
	ds_read_b128 v[244:247], v228
	ds_read_b128 v[220:223], v229
	s_waitcnt vmcnt(7)
	s_waitcnt lgkmcnt(0)
	v_lshlrev_b32_e32 v184, 16, v148
	v_and_b32_e32 v185, 0xffff0000, v148
	v_pk_mul_f32 v[244:245], v[244:245], v[184:185]
	v_lshlrev_b32_e32 v184, 16, v149
	v_and_b32_e32 v185, 0xffff0000, v149
	v_pk_mul_f32 v[246:247], v[246:247], v[184:185]
	v_lshlrev_b32_e32 v184, 16, v150
	v_and_b32_e32 v185, 0xffff0000, v150
	v_pk_mul_f32 v[220:221], v[220:221], v[184:185]
	v_lshlrev_b32_e32 v184, 16, v151
	v_and_b32_e32 v185, 0xffff0000, v151
	v_pk_mul_f32 v[222:223], v[222:223], v[184:185]
	v_cvt_pk_bf16_f32 v148, v244, v245
	v_cvt_pk_bf16_f32 v149, v246, v247
	v_cvt_pk_bf16_f32 v150, v220, v221
	v_cvt_pk_bf16_f32 v151, v222, v223
	v_add_u32_e32 v219, 0x5000, v218
	global_store_dwordx4 v219, v[148:151], s[24:25]
	v_add_u32_e32 v219, 12, v212
	v_and_b32_e32 v219, 7, v219
	v_xor_b32_e32 v219, v213, v219
	v_add_u32_e32 v228, 12, v215
	v_lshlrev_b32_e32 v228, 10, v228
	v_lshl_add_u32 v228, v219, 4, v228
	v_xor_b32_e32 v229, 16, v228
	ds_read_b128 v[244:247], v228
	ds_read_b128 v[220:223], v229
	s_waitcnt vmcnt(7)
	s_waitcnt lgkmcnt(0)
	v_lshlrev_b32_e32 v184, 16, v152
	v_and_b32_e32 v185, 0xffff0000, v152
	v_pk_mul_f32 v[244:245], v[244:245], v[184:185]
	v_lshlrev_b32_e32 v184, 16, v153
	v_and_b32_e32 v185, 0xffff0000, v153
	v_pk_mul_f32 v[246:247], v[246:247], v[184:185]
	v_lshlrev_b32_e32 v184, 16, v154
	v_and_b32_e32 v185, 0xffff0000, v154
	v_pk_mul_f32 v[220:221], v[220:221], v[184:185]
	v_lshlrev_b32_e32 v184, 16, v155
	v_and_b32_e32 v185, 0xffff0000, v155
	v_pk_mul_f32 v[222:223], v[222:223], v[184:185]
	v_cvt_pk_bf16_f32 v152, v244, v245
	v_cvt_pk_bf16_f32 v153, v246, v247
	v_cvt_pk_bf16_f32 v154, v220, v221
	v_cvt_pk_bf16_f32 v155, v222, v223
	v_add_u32_e32 v219, 0x6000, v218
	global_store_dwordx4 v219, v[152:155], s[24:25]
	v_add_u32_e32 v219, 14, v212
	v_and_b32_e32 v219, 7, v219
	v_xor_b32_e32 v219, v213, v219
	v_add_u32_e32 v228, 14, v215
	v_lshlrev_b32_e32 v228, 10, v228
	v_lshl_add_u32 v228, v219, 4, v228
	v_xor_b32_e32 v229, 16, v228
	ds_read_b128 v[244:247], v228
	ds_read_b128 v[220:223], v229
	s_waitcnt vmcnt(7)
	s_waitcnt lgkmcnt(0)
	v_lshlrev_b32_e32 v184, 16, v156
	v_and_b32_e32 v185, 0xffff0000, v156
	v_pk_mul_f32 v[244:245], v[244:245], v[184:185]
	v_lshlrev_b32_e32 v184, 16, v157
	v_and_b32_e32 v185, 0xffff0000, v157
	v_pk_mul_f32 v[246:247], v[246:247], v[184:185]
	v_lshlrev_b32_e32 v184, 16, v158
	v_and_b32_e32 v185, 0xffff0000, v158
	v_pk_mul_f32 v[220:221], v[220:221], v[184:185]
	v_lshlrev_b32_e32 v184, 16, v159
	v_and_b32_e32 v185, 0xffff0000, v159
	v_pk_mul_f32 v[222:223], v[222:223], v[184:185]
	v_cvt_pk_bf16_f32 v156, v244, v245
	v_cvt_pk_bf16_f32 v157, v246, v247
	v_cvt_pk_bf16_f32 v158, v220, v221
	v_cvt_pk_bf16_f32 v159, v222, v223
	v_add_u32_e32 v219, 0x7000, v218
	global_store_dwordx4 v219, v[156:159], s[24:25]
	s_barrier
	ds_write_b128 v210, v[60:63]
	ds_write_b128 v211, v[56:59]
	ds_write_b128 v210, v[52:55] offset:512
	ds_write_b128 v211, v[48:51] offset:512
	ds_write_b128 v210, v[44:47] offset:16384
	ds_write_b128 v211, v[40:43] offset:16384
	ds_write_b128 v210, v[36:39] offset:16896
	ds_write_b128 v211, v[32:35] offset:16896
	ds_write_b128 v210, v[28:31] offset:32768
	ds_write_b128 v211, v[24:27] offset:32768
	ds_write_b128 v210, v[20:23] offset:33280
	ds_write_b128 v211, v[16:19] offset:33280
	ds_write_b128 v210, v[12:15] offset:49152
	ds_write_b128 v211, v[8:11] offset:49152
	ds_write_b128 v210, v[4:7] offset:49664
	ds_write_b128 v211, v[0:3] offset:49664
	s_waitcnt lgkmcnt(0)
	s_barrier
; #define EPI_COL(u) (EPI_CB(u) + 8 * fq)
; DI u32x4 pack8(const float* v) { u32x4 w; w.x = pk2(v[0], v[1]); w.y = pk2(v[2], v[3]); w.z = pk2(v[4], v[5]); w.w = pk2(v[6], v[7]); return w; }
;     DI void operator()(const Acc& acc, const Unit& u, int wr, int wc, int fr, int fq) const {
;     ...
;             const int row = EPI_ROW(u), col = EPI_COL(u); EPI_V(v);
;             const u32x4 gg = *(const u32x4*)(gate + (size_t)row * 3072 + gi * 1024 + col);
;             const float gf[8] = {bflo(gg.x), bfhi(gg.x), bflo(gg.y), bfhi(gg.y), bflo(gg.z), bfhi(gg.z), bflo(gg.w), bfhi(gg.w)};
;             bf16_t* mp = mrg + (size_t)row * 1024 + col;
;             if (accum) {
;                 const u32x4 oo = *(const u32x4*)mp;
;                 const float of[8] = {bflo(oo.x), bfhi(oo.x), bflo(oo.y), bfhi(oo.y), bflo(oo.z), bfhi(oo.z), bflo(oo.w), bfhi(oo.w)};
; #pragma unroll
;                 for (int j = 0; j < 8; ++j) v[j] = of[j] + gf[j] * v[j];
;             } else {
; #pragma unroll
;                 for (int j = 0; j < 8; ++j) v[j] = gf[j] * v[j];
;             }
;             *(u32x4*)mp = pack8(v);
	v_add_u32_e32 v215, s7, v212
	s_add_i32 s8, s2, 128
	v_add_u32_e32 v216, s8, v215
	v_mul_u32_u24_e32 v217, 0x1800, v216
	v_add_u32_e32 v217, v217, v214
	v_add_u32_e32 v217, 0x0, v217
	v_lshl_add_u32 v218, v216, 11, v214
	global_load_dwordx4 v[128:131], v217, s[22:23]
	v_add_u32_e32 v219, 0x3000, v217
	global_load_dwordx4 v[132:135], v219, s[22:23]
	v_add_u32_e32 v219, 0x6000, v217
	global_load_dwordx4 v[136:139], v219, s[22:23]
	v_add_u32_e32 v219, 0x9000, v217
	global_load_dwordx4 v[140:143], v219, s[22:23]
	v_add_u32_e32 v219, 0xc000, v217
	global_load_dwordx4 v[144:147], v219, s[22:23]
	v_add_u32_e32 v219, 0xf000, v217
	global_load_dwordx4 v[148:151], v219, s[22:23]
	v_add_u32_e32 v219, 0x12000, v217
	global_load_dwordx4 v[152:155], v219, s[22:23]
	v_add_u32_e32 v219, 0x15000, v217
	global_load_dwordx4 v[156:159], v219, s[22:23]
	v_add_u32_e32 v219, 0, v212
	v_and_b32_e32 v219, 7, v219
	v_xor_b32_e32 v219, v213, v219
	v_add_u32_e32 v228, 0, v215
	v_lshlrev_b32_e32 v228, 10, v228
	v_lshl_add_u32 v228, v219, 4, v228
	v_xor_b32_e32 v229, 16, v228
	ds_read_b128 v[244:247], v228
	ds_read_b128 v[220:223], v229
	s_waitcnt vmcnt(7)
	s_waitcnt lgkmcnt(0)
	v_lshlrev_b32_e32 v184, 16, v128
	v_and_b32_e32 v185, 0xffff0000, v128
	v_pk_mul_f32 v[244:245], v[244:245], v[184:185]
	v_lshlrev_b32_e32 v184, 16, v129
	v_and_b32_e32 v185, 0xffff0000, v129
	v_pk_mul_f32 v[246:247], v[246:247], v[184:185]
	v_lshlrev_b32_e32 v184, 16, v130
	v_and_b32_e32 v185, 0xffff0000, v130
	v_pk_mul_f32 v[220:221], v[220:221], v[184:185]
	v_lshlrev_b32_e32 v184, 16, v131
	v_and_b32_e32 v185, 0xffff0000, v131
	v_pk_mul_f32 v[222:223], v[222:223], v[184:185]
	v_cvt_pk_bf16_f32 v128, v244, v245
	v_cvt_pk_bf16_f32 v129, v246, v247
	v_cvt_pk_bf16_f32 v130, v220, v221
	v_cvt_pk_bf16_f32 v131, v222, v223
	global_store_dwordx4 v218, v[128:131], s[24:25]
	v_add_u32_e32 v219, 2, v212
	v_and_b32_e32 v219, 7, v219
	v_xor_b32_e32 v219, v213, v219
	v_add_u32_e32 v228, 2, v215
	v_lshlrev_b32_e32 v228, 10, v228
	v_lshl_add_u32 v228, v219, 4, v228
	v_xor_b32_e32 v229, 16, v228
	ds_read_b128 v[244:247], v228
	ds_read_b128 v[220:223], v229
	s_waitcnt vmcnt(7)
	s_waitcnt lgkmcnt(0)
	v_lshlrev_b32_e32 v184, 16, v132
	v_and_b32_e32 v185, 0xffff0000, v132
	v_pk_mul_f32 v[244:245], v[244:245], v[184:185]
	v_lshlrev_b32_e32 v184, 16, v133
	v_and_b32_e32 v185, 0xffff0000, v133
	v_pk_mul_f32 v[246:247], v[246:247], v[184:185]
	v_lshlrev_b32_e32 v184, 16, v134
	v_and_b32_e32 v185, 0xffff0000, v134
	v_pk_mul_f32 v[220:221], v[220:221], v[184:185]
	v_lshlrev_b32_e32 v184, 16, v135
	v_and_b32_e32 v185, 0xffff0000, v135
	v_pk_mul_f32 v[222:223], v[222:223], v[184:185]
	v_cvt_pk_bf16_f32 v132, v244, v245
	v_cvt_pk_bf16_f32 v133, v246, v247
	v_cvt_pk_bf16_f32 v134, v220, v221
	v_cvt_pk_bf16_f32 v135, v222, v223
	v_add_u32_e32 v219, 0x1000, v218
	global_store_dwordx4 v219, v[132:135], s[24:25]
	v_add_u32_e32 v219, 4, v212
	v_and_b32_e32 v219, 7, v219
	v_xor_b32_e32 v219, v213, v219
	v_add_u32_e32 v228, 4, v215
	v_lshlrev_b32_e32 v228, 10, v228
	v_lshl_add_u32 v228, v219, 4, v228
	v_xor_b32_e32 v229, 16, v228
	ds_read_b128 v[244:247], v228
	ds_read_b128 v[220:223], v229
	s_waitcnt vmcnt(7)
	s_waitcnt lgkmcnt(0)
	v_lshlrev_b32_e32 v184, 16, v136
	v_and_b32_e32 v185, 0xffff0000, v136
	v_pk_mul_f32 v[244:245], v[244:245], v[184:185]
	v_lshlrev_b32_e32 v184, 16, v137
	v_and_b32_e32 v185, 0xffff0000, v137
	v_pk_mul_f32 v[246:247], v[246:247], v[184:185]
	v_lshlrev_b32_e32 v184, 16, v138
	v_and_b32_e32 v185, 0xffff0000, v138
	v_pk_mul_f32 v[220:221], v[220:221], v[184:185]
	v_lshlrev_b32_e32 v184, 16, v139
	v_and_b32_e32 v185, 0xffff0000, v139
	v_pk_mul_f32 v[222:223], v[222:223], v[184:185]
	v_cvt_pk_bf16_f32 v136, v244, v245
	v_cvt_pk_bf16_f32 v137, v246, v247
	v_cvt_pk_bf16_f32 v138, v220, v221
	v_cvt_pk_bf16_f32 v139, v222, v223
	v_add_u32_e32 v219, 0x2000, v218
	global_store_dwordx4 v219, v[136:139], s[24:25]
	v_add_u32_e32 v219, 6, v212
	v_and_b32_e32 v219, 7, v219
	v_xor_b32_e32 v219, v213, v219
	v_add_u32_e32 v228, 6, v215
	v_lshlrev_b32_e32 v228, 10, v228
	v_lshl_add_u32 v228, v219, 4, v228
	v_xor_b32_e32 v229, 16, v228
	ds_read_b128 v[244:247], v228
	ds_read_b128 v[220:223], v229
	s_waitcnt vmcnt(7)
	s_waitcnt lgkmcnt(0)
; #define PG8_BAR __builtin_amdgcn_s_barrier()
; #define EPI_COL(u) (EPI_CB(u) + 8 * fq)
; DI u32x4 pack8(const float* v) { u32x4 w; w.x = pk2(v[0], v[1]); w.y = pk2(v[2], v[3]); w.z = pk2(v[4], v[5]); w.w = pk2(v[6], v[7]); return w; }
; template <class Epi>
; DI void gemm_phase(LAS unsigned char* lds, const Gemm g, const Sched& S, const Epi& E) {
;     ...
;         if (!has_next) break;
; #pragma unroll
;         for (int a = 0; a < 2; ++a)
; #pragma unroll
;             for (int b = 0; b < 2; ++b)
; #pragma unroll
;                 for (int m = 0; m < 4; ++m)
; #pragma unroll
;                     for (int n = 0; n < 2; ++n) acc[a][b][m][n] = (f32x4){0.f, 0.f, 0.f, 0.f};
;         cur = nxt; cA = nA; cB = nB; ++ui;
;         if (wr == 1) PG8_BAR;
;     DI void operator()(const Acc& acc, const Unit& u, int wr, int wc, int fr, int fq) const {
;     ...
;             const int row = EPI_ROW(u), col = EPI_COL(u); EPI_V(v);
;             const u32x4 gg = *(const u32x4*)(gate + (size_t)row * 3072 + gi * 1024 + col);
;             const float gf[8] = {bflo(gg.x), bfhi(gg.x), bflo(gg.y), bfhi(gg.y), bflo(gg.z), bfhi(gg.z), bflo(gg.w), bfhi(gg.w)};
;             bf16_t* mp = mrg + (size_t)row * 1024 + col;
;             if (accum) {
;                 const u32x4 oo = *(const u32x4*)mp;
;                 const float of[8] = {bflo(oo.x), bfhi(oo.x), bflo(oo.y), bfhi(oo.y), bflo(oo.z), bfhi(oo.z), bflo(oo.w), bfhi(oo.w)};
; #pragma unroll
;                 for (int j = 0; j < 8; ++j) v[j] = of[j] + gf[j] * v[j];
;             } else {
; #pragma unroll
;                 for (int j = 0; j < 8; ++j) v[j] = gf[j] * v[j];
;             }
;             *(u32x4*)mp = pack8(v);
	v_lshlrev_b32_e32 v184, 16, v140
	v_and_b32_e32 v185, 0xffff0000, v140
	v_pk_mul_f32 v[244:245], v[244:245], v[184:185]
	v_lshlrev_b32_e32 v184, 16, v141
	v_and_b32_e32 v185, 0xffff0000, v141
	v_pk_mul_f32 v[246:247], v[246:247], v[184:185]
	v_lshlrev_b32_e32 v184, 16, v142
	v_and_b32_e32 v185, 0xffff0000, v142
	v_pk_mul_f32 v[220:221], v[220:221], v[184:185]
	v_lshlrev_b32_e32 v184, 16, v143
	v_and_b32_e32 v185, 0xffff0000, v143
	v_pk_mul_f32 v[222:223], v[222:223], v[184:185]
	v_cvt_pk_bf16_f32 v140, v244, v245
	v_cvt_pk_bf16_f32 v141, v246, v247
	v_cvt_pk_bf16_f32 v142, v220, v221
	v_cvt_pk_bf16_f32 v143, v222, v223
	v_add_u32_e32 v219, 0x3000, v218
	global_store_dwordx4 v219, v[140:143], s[24:25]
	v_add_u32_e32 v219, 8, v212
	v_and_b32_e32 v219, 7, v219
	v_xor_b32_e32 v219, v213, v219
	v_add_u32_e32 v228, 8, v215
	v_lshlrev_b32_e32 v228, 10, v228
	v_lshl_add_u32 v228, v219, 4, v228
	v_xor_b32_e32 v229, 16, v228
	ds_read_b128 v[244:247], v228
	ds_read_b128 v[220:223], v229
	s_waitcnt vmcnt(7)
	s_waitcnt lgkmcnt(0)
	v_lshlrev_b32_e32 v184, 16, v144
	v_and_b32_e32 v185, 0xffff0000, v144
	v_pk_mul_f32 v[244:245], v[244:245], v[184:185]
	v_lshlrev_b32_e32 v184, 16, v145
	v_and_b32_e32 v185, 0xffff0000, v145
	v_pk_mul_f32 v[246:247], v[246:247], v[184:185]
	v_lshlrev_b32_e32 v184, 16, v146
	v_and_b32_e32 v185, 0xffff0000, v146
	v_pk_mul_f32 v[220:221], v[220:221], v[184:185]
	v_lshlrev_b32_e32 v184, 16, v147
	v_and_b32_e32 v185, 0xffff0000, v147
	v_pk_mul_f32 v[222:223], v[222:223], v[184:185]
	v_cvt_pk_bf16_f32 v144, v244, v245
	v_cvt_pk_bf16_f32 v145, v246, v247
	v_cvt_pk_bf16_f32 v146, v220, v221
	v_cvt_pk_bf16_f32 v147, v222, v223
	v_add_u32_e32 v219, 0x4000, v218
	global_store_dwordx4 v219, v[144:147], s[24:25]
	v_add_u32_e32 v219, 10, v212
	v_and_b32_e32 v219, 7, v219
	v_xor_b32_e32 v219, v213, v219
	v_add_u32_e32 v228, 10, v215
	v_lshlrev_b32_e32 v228, 10, v228
	v_lshl_add_u32 v228, v219, 4, v228
	v_xor_b32_e32 v229, 16, v228
	ds_read_b128 v[244:247], v228
	ds_read_b128 v[220:223], v229
	s_waitcnt vmcnt(7)
	s_waitcnt lgkmcnt(0)
	v_lshlrev_b32_e32 v184, 16, v148
	v_and_b32_e32 v185, 0xffff0000, v148
	v_pk_mul_f32 v[244:245], v[244:245], v[184:185]
	v_lshlrev_b32_e32 v184, 16, v149
	v_and_b32_e32 v185, 0xffff0000, v149
	v_pk_mul_f32 v[246:247], v[246:247], v[184:185]
	v_lshlrev_b32_e32 v184, 16, v150
	v_and_b32_e32 v185, 0xffff0000, v150
	v_pk_mul_f32 v[220:221], v[220:221], v[184:185]
	v_lshlrev_b32_e32 v184, 16, v151
	v_and_b32_e32 v185, 0xffff0000, v151
	v_pk_mul_f32 v[222:223], v[222:223], v[184:185]
	v_cvt_pk_bf16_f32 v148, v244, v245
	v_cvt_pk_bf16_f32 v149, v246, v247
	v_cvt_pk_bf16_f32 v150, v220, v221
	v_cvt_pk_bf16_f32 v151, v222, v223
	v_add_u32_e32 v219, 0x5000, v218
	global_store_dwordx4 v219, v[148:151], s[24:25]
	v_add_u32_e32 v219, 12, v212
	v_and_b32_e32 v219, 7, v219
	v_xor_b32_e32 v219, v213, v219
	v_add_u32_e32 v228, 12, v215
	v_lshlrev_b32_e32 v228, 10, v228
	v_lshl_add_u32 v228, v219, 4, v228
	v_xor_b32_e32 v229, 16, v228
	ds_read_b128 v[244:247], v228
	ds_read_b128 v[220:223], v229
	s_waitcnt vmcnt(7)
	s_waitcnt lgkmcnt(0)
	v_lshlrev_b32_e32 v184, 16, v152
	v_and_b32_e32 v185, 0xffff0000, v152
	v_pk_mul_f32 v[244:245], v[244:245], v[184:185]
	v_lshlrev_b32_e32 v184, 16, v153
	v_and_b32_e32 v185, 0xffff0000, v153
	v_pk_mul_f32 v[246:247], v[246:247], v[184:185]
	v_lshlrev_b32_e32 v184, 16, v154
	v_and_b32_e32 v185, 0xffff0000, v154
	v_pk_mul_f32 v[220:221], v[220:221], v[184:185]
	v_lshlrev_b32_e32 v184, 16, v155
	v_and_b32_e32 v185, 0xffff0000, v155
	v_pk_mul_f32 v[222:223], v[222:223], v[184:185]
	v_cvt_pk_bf16_f32 v152, v244, v245
	v_cvt_pk_bf16_f32 v153, v246, v247
	v_cvt_pk_bf16_f32 v154, v220, v221
	v_cvt_pk_bf16_f32 v155, v222, v223
	v_add_u32_e32 v219, 0x6000, v218
	global_store_dwordx4 v219, v[152:155], s[24:25]
	v_add_u32_e32 v219, 14, v212
	v_and_b32_e32 v219, 7, v219
	v_xor_b32_e32 v219, v213, v219
	v_add_u32_e32 v228, 14, v215
	v_lshlrev_b32_e32 v228, 10, v228
	v_lshl_add_u32 v228, v219, 4, v228
	v_xor_b32_e32 v229, 16, v228
	ds_read_b128 v[244:247], v228
	ds_read_b128 v[220:223], v229
	s_waitcnt vmcnt(7)
	s_waitcnt lgkmcnt(0)
	v_lshlrev_b32_e32 v184, 16, v156
	v_and_b32_e32 v185, 0xffff0000, v156
	v_pk_mul_f32 v[244:245], v[244:245], v[184:185]
	v_lshlrev_b32_e32 v184, 16, v157
	v_and_b32_e32 v185, 0xffff0000, v157
	v_pk_mul_f32 v[246:247], v[246:247], v[184:185]
	v_lshlrev_b32_e32 v184, 16, v158
	v_and_b32_e32 v185, 0xffff0000, v158
	v_pk_mul_f32 v[220:221], v[220:221], v[184:185]
	v_lshlrev_b32_e32 v184, 16, v159
	v_and_b32_e32 v185, 0xffff0000, v159
	v_pk_mul_f32 v[222:223], v[222:223], v[184:185]
	v_cvt_pk_bf16_f32 v156, v244, v245
	v_cvt_pk_bf16_f32 v157, v246, v247
	v_cvt_pk_bf16_f32 v158, v220, v221
	v_cvt_pk_bf16_f32 v159, v222, v223
	v_add_u32_e32 v219, 0x7000, v218
	global_store_dwordx4 v219, v[156:159], s[24:25]
	s_mov_b64 s[6:7], -1
	s_and_b64 vcc, exec, s[14:15]
	s_cbranch_vccnz .LBB0_1046
	s_andn2_b64 vcc, exec, s[20:21]
	s_cbranch_vccnz .LBB0_1045
	s_barrier
	s_branch .LBB0_1045

; #define EPI_FOR(u) \
;     _Pragma("unroll") for (int ai = 0; ai < 2; ++ai) _Pragma("unroll") for (int m = 0; m < 4; ++m) _Pragma("unroll") for (int bj = 0; bj < 2; ++bj)
; #define EPI_COL(u) (EPI_CB(u) + 8 * fq)
;     DI void operator()(const Acc& acc, const Unit& u, int wr, int wc, int fr, int fq) const {
;         EPI_FOR(u) {
;             const int row = EPI_ROW(u), col = EPI_COL(u); EPI_V(v);
;             const u32x4 gg = *(const u32x4*)(gate + (size_t)row * 3072 + gi * 1024 + col);
;             const float gf[8] = {bflo(gg.x), bfhi(gg.x), bflo(gg.y), bfhi(gg.y), bflo(gg.z), bfhi(gg.z), bflo(gg.w), bfhi(gg.w)};
;             bf16_t* mp = mrg + (size_t)row * 1024 + col;
;             if (accum) {
;                 const u32x4 oo = *(const u32x4*)mp;
;                 const float of[8] = {bflo(oo.x), bfhi(oo.x), bflo(oo.y), bfhi(oo.y), bflo(oo.z), bfhi(oo.z), bflo(oo.w), bfhi(oo.w)};
; #pragma unroll
;                 for (int j = 0; j < 8; ++j) v[j] = of[j] + gf[j] * v[j];
.LBB0_1222:
	s_lshl_b32 s2, s44, 8
	s_lshl_b32 s6, s28, 8
	v_readfirstlane_b32 s7, v232
	s_lshr_b32 s7, s7, 6
	s_lshl_b32 s7, s7, 4
	v_add_u32_e32 v210, s64, v145
	v_lshlrev_b32_e32 v210, 10, v210
	v_and_b32_e32 v211, 7, v145
	v_lshlrev_b32_e32 v212, 1, v144
	v_xor_b32_e32 v211, v212, v211
	v_lshl_add_u32 v210, v211, 4, v210
	s_lshl_b32 s8, s65, 2
	v_add_u32_e32 v210, s8, v210
	v_xor_b32_e32 v211, 16, v210
	v_lshrrev_b32_e32 v212, 5, v233
	v_and_b32_e32 v213, 31, v233
	v_lshl_add_u32 v214, v213, 3, s6
	v_lshlrev_b32_e32 v214, 1, v214
	v_lshlrev_b32_e32 v213, 1, v213
	s_waitcnt vmcnt(0)
	s_barrier
	ds_write_b128 v210, v[124:127]
	ds_write_b128 v211, v[120:123]
	ds_write_b128 v210, v[116:119] offset:512
	ds_write_b128 v211, v[112:115] offset:512
	ds_write_b128 v210, v[108:111] offset:16384
	ds_write_b128 v211, v[104:107] offset:16384
	ds_write_b128 v210, v[100:103] offset:16896
	ds_write_b128 v211, v[96:99] offset:16896
	ds_write_b128 v210, v[92:95] offset:32768
	ds_write_b128 v211, v[88:91] offset:32768
	ds_write_b128 v210, v[84:87] offset:33280
	ds_write_b128 v211, v[80:83] offset:33280
	ds_write_b128 v210, v[76:79] offset:49152
	ds_write_b128 v211, v[72:75] offset:49152
	ds_write_b128 v210, v[68:71] offset:49664
	ds_write_b128 v211, v[64:67] offset:49664
	s_waitcnt lgkmcnt(0)
	s_barrier
	v_add_u32_e32 v215, s7, v212
	s_add_i32 s8, s2, 0
	v_add_u32_e32 v216, s8, v215
	v_mul_u32_u24_e32 v217, 0x1800, v216
	v_add_u32_e32 v217, v217, v214
	v_add_u32_e32 v217, 0x1000, v217
	v_lshl_add_u32 v218, v216, 11, v214
	global_load_dwordx4 v[128:131], v217, s[20:21]
	global_load_dwordx4 v[160:163], v218, s[22:23]
	v_add_u32_e32 v219, 0x3000, v217
	global_load_dwordx4 v[132:135], v219, s[20:21]
	v_add_u32_e32 v219, 0x1000, v218
	global_load_dwordx4 v[164:167], v219, s[22:23]
	v_add_u32_e32 v219, 0x6000, v217
	global_load_dwordx4 v[136:139], v219, s[20:21]
	v_add_u32_e32 v219, 0x2000, v218
	global_load_dwordx4 v[168:171], v219, s[22:23]
	v_add_u32_e32 v219, 0x9000, v217
	global_load_dwordx4 v[140:143], v219, s[20:21]
	v_add_u32_e32 v219, 0x3000, v218
	global_load_dwordx4 v[172:175], v219, s[22:23]
	v_add_u32_e32 v219, 0xc000, v217
	global_load_dwordx4 v[144:147], v219, s[20:21]
	v_add_u32_e32 v219, 0x4000, v218
	global_load_dwordx4 v[176:179], v219, s[22:23]
	v_add_u32_e32 v219, 0xf000, v217
	global_load_dwordx4 v[148:151], v219, s[20:21]
	v_add_u32_e32 v219, 0x5000, v218
	global_load_dwordx4 v[180:183], v219, s[22:23]
	v_add_u32_e32 v219, 0x12000, v217
	global_load_dwordx4 v[152:155], v219, s[20:21]
	v_add_u32_e32 v219, 0x6000, v218
	global_load_dwordx4 v[224:227], v219, s[22:23]
	v_add_u32_e32 v219, 0x15000, v217
	global_load_dwordx4 v[156:159], v219, s[20:21]
	v_add_u32_e32 v219, 0x7000, v218
	global_load_dwordx4 v[240:243], v219, s[22:23]
	v_add_u32_e32 v219, 0, v212
	v_and_b32_e32 v219, 7, v219
	v_xor_b32_e32 v219, v213, v219
	v_add_u32_e32 v228, 0, v215
	v_lshlrev_b32_e32 v228, 10, v228
	v_lshl_add_u32 v228, v219, 4, v228
	v_xor_b32_e32 v229, 16, v228
	ds_read_b128 v[244:247], v228
	ds_read_b128 v[220:223], v229
	s_waitcnt vmcnt(14)
	s_waitcnt lgkmcnt(0)
	v_lshlrev_b32_e32 v184, 16, v128
	v_and_b32_e32 v185, 0xffff0000, v128
	v_lshlrev_b32_e32 v186, 16, v160
	v_and_b32_e32 v187, 0xffff0000, v160
	v_pk_fma_f32 v[244:245], v[244:245], v[184:185], v[186:187]
	v_lshlrev_b32_e32 v184, 16, v129
	v_and_b32_e32 v185, 0xffff0000, v129
	v_lshlrev_b32_e32 v186, 16, v161
	v_and_b32_e32 v187, 0xffff0000, v161
	v_pk_fma_f32 v[246:247], v[246:247], v[184:185], v[186:187]
	v_lshlrev_b32_e32 v184, 16, v130
	v_and_b32_e32 v185, 0xffff0000, v130
	v_lshlrev_b32_e32 v186, 16, v162
	v_and_b32_e32 v187, 0xffff0000, v162
	v_pk_fma_f32 v[220:221], v[220:221], v[184:185], v[186:187]
	v_lshlrev_b32_e32 v184, 16, v131
	v_and_b32_e32 v185, 0xffff0000, v131
	v_lshlrev_b32_e32 v186, 16, v163
	v_and_b32_e32 v187, 0xffff0000, v163
	v_pk_fma_f32 v[222:223], v[222:223], v[184:185], v[186:187]
	v_cvt_pk_bf16_f32 v128, v244, v245
	v_cvt_pk_bf16_f32 v129, v246, v247
	v_cvt_pk_bf16_f32 v130, v220, v221
	v_cvt_pk_bf16_f32 v131, v222, v223
	global_store_dwordx4 v218, v[128:131], s[22:23]
	v_add_u32_e32 v219, 2, v212
	v_and_b32_e32 v219, 7, v219
	v_xor_b32_e32 v219, v213, v219
	v_add_u32_e32 v228, 2, v215
	v_lshlrev_b32_e32 v228, 10, v228
	v_lshl_add_u32 v228, v219, 4, v228
	v_xor_b32_e32 v229, 16, v228
	ds_read_b128 v[244:247], v228
	ds_read_b128 v[220:223], v229
	s_waitcnt vmcnt(13)
	s_waitcnt lgkmcnt(0)
	v_lshlrev_b32_e32 v184, 16, v132
	v_and_b32_e32 v185, 0xffff0000, v132
	v_lshlrev_b32_e32 v186, 16, v164
	v_and_b32_e32 v187, 0xffff0000, v164
	v_pk_fma_f32 v[244:245], v[244:245], v[184:185], v[186:187]
	v_lshlrev_b32_e32 v184, 16, v133
	v_and_b32_e32 v185, 0xffff0000, v133
	v_lshlrev_b32_e32 v186, 16, v165
	v_and_b32_e32 v187, 0xffff0000, v165
	v_pk_fma_f32 v[246:247], v[246:247], v[184:185], v[186:187]
	v_lshlrev_b32_e32 v184, 16, v134
	v_and_b32_e32 v185, 0xffff0000, v134
	v_lshlrev_b32_e32 v186, 16, v166
	v_and_b32_e32 v187, 0xffff0000, v166
	v_pk_fma_f32 v[220:221], v[220:221], v[184:185], v[186:187]
	v_lshlrev_b32_e32 v184, 16, v135
	v_and_b32_e32 v185, 0xffff0000, v135
	v_lshlrev_b32_e32 v186, 16, v167
	v_and_b32_e32 v187, 0xffff0000, v167
	v_pk_fma_f32 v[222:223], v[222:223], v[184:185], v[186:187]
	v_cvt_pk_bf16_f32 v132, v244, v245
	v_cvt_pk_bf16_f32 v133, v246, v247
	v_cvt_pk_bf16_f32 v134, v220, v221
	v_cvt_pk_bf16_f32 v135, v222, v223
	v_add_u32_e32 v219, 0x1000, v218
	global_store_dwordx4 v219, v[132:135], s[22:23]
	v_add_u32_e32 v219, 4, v212
	v_and_b32_e32 v219, 7, v219
	v_xor_b32_e32 v219, v213, v219
	v_add_u32_e32 v228, 4, v215
	v_lshlrev_b32_e32 v228, 10, v228
	v_lshl_add_u32 v228, v219, 4, v228
	v_xor_b32_e32 v229, 16, v228
	ds_read_b128 v[244:247], v228
	ds_read_b128 v[220:223], v229
	s_waitcnt vmcnt(12)
; #define EPI_COL(u) (EPI_CB(u) + 8 * fq)
;     DI void operator()(const Acc& acc, const Unit& u, int wr, int wc, int fr, int fq) const {
;     ...
;             const int row = EPI_ROW(u), col = EPI_COL(u); EPI_V(v);
;             const u32x4 gg = *(const u32x4*)(gate + (size_t)row * 3072 + gi * 1024 + col);
;             const float gf[8] = {bflo(gg.x), bfhi(gg.x), bflo(gg.y), bfhi(gg.y), bflo(gg.z), bfhi(gg.z), bflo(gg.w), bfhi(gg.w)};
;             bf16_t* mp = mrg + (size_t)row * 1024 + col;
;             if (accum) {
;                 const u32x4 oo = *(const u32x4*)mp;
;                 const float of[8] = {bflo(oo.x), bfhi(oo.x), bflo(oo.y), bfhi(oo.y), bflo(oo.z), bfhi(oo.z), bflo(oo.w), bfhi(oo.w)};
; #pragma unroll
;                 for (int j = 0; j < 8; ++j) v[j] = of[j] + gf[j] * v[j];
	s_waitcnt lgkmcnt(0)
	v_lshlrev_b32_e32 v184, 16, v136
	v_and_b32_e32 v185, 0xffff0000, v136
	v_lshlrev_b32_e32 v186, 16, v168
	v_and_b32_e32 v187, 0xffff0000, v168
	v_pk_fma_f32 v[244:245], v[244:245], v[184:185], v[186:187]
	v_lshlrev_b32_e32 v184, 16, v137
	v_and_b32_e32 v185, 0xffff0000, v137
	v_lshlrev_b32_e32 v186, 16, v169
	v_and_b32_e32 v187, 0xffff0000, v169
	v_pk_fma_f32 v[246:247], v[246:247], v[184:185], v[186:187]
	v_lshlrev_b32_e32 v184, 16, v138
	v_and_b32_e32 v185, 0xffff0000, v138
	v_lshlrev_b32_e32 v186, 16, v170
	v_and_b32_e32 v187, 0xffff0000, v170
	v_pk_fma_f32 v[220:221], v[220:221], v[184:185], v[186:187]
	v_lshlrev_b32_e32 v184, 16, v139
	v_and_b32_e32 v185, 0xffff0000, v139
	v_lshlrev_b32_e32 v186, 16, v171
	v_and_b32_e32 v187, 0xffff0000, v171
	v_pk_fma_f32 v[222:223], v[222:223], v[184:185], v[186:187]
	v_cvt_pk_bf16_f32 v136, v244, v245
	v_cvt_pk_bf16_f32 v137, v246, v247
	v_cvt_pk_bf16_f32 v138, v220, v221
	v_cvt_pk_bf16_f32 v139, v222, v223
	v_add_u32_e32 v219, 0x2000, v218
	global_store_dwordx4 v219, v[136:139], s[22:23]
	v_add_u32_e32 v219, 6, v212
	v_and_b32_e32 v219, 7, v219
	v_xor_b32_e32 v219, v213, v219
	v_add_u32_e32 v228, 6, v215
	v_lshlrev_b32_e32 v228, 10, v228
	v_lshl_add_u32 v228, v219, 4, v228
	v_xor_b32_e32 v229, 16, v228
	ds_read_b128 v[244:247], v228
	ds_read_b128 v[220:223], v229
	s_waitcnt vmcnt(11)
	s_waitcnt lgkmcnt(0)
	v_lshlrev_b32_e32 v184, 16, v140
	v_and_b32_e32 v185, 0xffff0000, v140
	v_lshlrev_b32_e32 v186, 16, v172
	v_and_b32_e32 v187, 0xffff0000, v172
	v_pk_fma_f32 v[244:245], v[244:245], v[184:185], v[186:187]
	v_lshlrev_b32_e32 v184, 16, v141
	v_and_b32_e32 v185, 0xffff0000, v141
	v_lshlrev_b32_e32 v186, 16, v173
	v_and_b32_e32 v187, 0xffff0000, v173
	v_pk_fma_f32 v[246:247], v[246:247], v[184:185], v[186:187]
	v_lshlrev_b32_e32 v184, 16, v142
	v_and_b32_e32 v185, 0xffff0000, v142
	v_lshlrev_b32_e32 v186, 16, v174
	v_and_b32_e32 v187, 0xffff0000, v174
	v_pk_fma_f32 v[220:221], v[220:221], v[184:185], v[186:187]
	v_lshlrev_b32_e32 v184, 16, v143
	v_and_b32_e32 v185, 0xffff0000, v143
	v_lshlrev_b32_e32 v186, 16, v175
	v_and_b32_e32 v187, 0xffff0000, v175
	v_pk_fma_f32 v[222:223], v[222:223], v[184:185], v[186:187]
	v_cvt_pk_bf16_f32 v140, v244, v245
	v_cvt_pk_bf16_f32 v141, v246, v247
	v_cvt_pk_bf16_f32 v142, v220, v221
	v_cvt_pk_bf16_f32 v143, v222, v223
	v_add_u32_e32 v219, 0x3000, v218
	global_store_dwordx4 v219, v[140:143], s[22:23]
	v_add_u32_e32 v219, 8, v212
	v_and_b32_e32 v219, 7, v219
	v_xor_b32_e32 v219, v213, v219
	v_add_u32_e32 v228, 8, v215
	v_lshlrev_b32_e32 v228, 10, v228
	v_lshl_add_u32 v228, v219, 4, v228
	v_xor_b32_e32 v229, 16, v228
	ds_read_b128 v[244:247], v228
	ds_read_b128 v[220:223], v229
	s_waitcnt vmcnt(10)
	s_waitcnt lgkmcnt(0)
	v_lshlrev_b32_e32 v184, 16, v144
	v_and_b32_e32 v185, 0xffff0000, v144
	v_lshlrev_b32_e32 v186, 16, v176
	v_and_b32_e32 v187, 0xffff0000, v176
	v_pk_fma_f32 v[244:245], v[244:245], v[184:185], v[186:187]
	v_lshlrev_b32_e32 v184, 16, v145
	v_and_b32_e32 v185, 0xffff0000, v145
	v_lshlrev_b32_e32 v186, 16, v177
	v_and_b32_e32 v187, 0xffff0000, v177
	v_pk_fma_f32 v[246:247], v[246:247], v[184:185], v[186:187]
	v_lshlrev_b32_e32 v184, 16, v146
	v_and_b32_e32 v185, 0xffff0000, v146
	v_lshlrev_b32_e32 v186, 16, v178
	v_and_b32_e32 v187, 0xffff0000, v178
	v_pk_fma_f32 v[220:221], v[220:221], v[184:185], v[186:187]
	v_lshlrev_b32_e32 v184, 16, v147
	v_and_b32_e32 v185, 0xffff0000, v147
	v_lshlrev_b32_e32 v186, 16, v179
	v_and_b32_e32 v187, 0xffff0000, v179
	v_pk_fma_f32 v[222:223], v[222:223], v[184:185], v[186:187]
	v_cvt_pk_bf16_f32 v144, v244, v245
	v_cvt_pk_bf16_f32 v145, v246, v247
	v_cvt_pk_bf16_f32 v146, v220, v221
	v_cvt_pk_bf16_f32 v147, v222, v223
	v_add_u32_e32 v219, 0x4000, v218
	global_store_dwordx4 v219, v[144:147], s[22:23]
	v_add_u32_e32 v219, 10, v212
	v_and_b32_e32 v219, 7, v219
	v_xor_b32_e32 v219, v213, v219
	v_add_u32_e32 v228, 10, v215
	v_lshlrev_b32_e32 v228, 10, v228
	v_lshl_add_u32 v228, v219, 4, v228
	v_xor_b32_e32 v229, 16, v228
	ds_read_b128 v[244:247], v228
	ds_read_b128 v[220:223], v229
	s_waitcnt vmcnt(9)
	s_waitcnt lgkmcnt(0)
	v_lshlrev_b32_e32 v184, 16, v148
	v_and_b32_e32 v185, 0xffff0000, v148
	v_lshlrev_b32_e32 v186, 16, v180
	v_and_b32_e32 v187, 0xffff0000, v180
	v_pk_fma_f32 v[244:245], v[244:245], v[184:185], v[186:187]
	v_lshlrev_b32_e32 v184, 16, v149
	v_and_b32_e32 v185, 0xffff0000, v149
	v_lshlrev_b32_e32 v186, 16, v181
	v_and_b32_e32 v187, 0xffff0000, v181
	v_pk_fma_f32 v[246:247], v[246:247], v[184:185], v[186:187]
	v_lshlrev_b32_e32 v184, 16, v150
	v_and_b32_e32 v185, 0xffff0000, v150
	v_lshlrev_b32_e32 v186, 16, v182
	v_and_b32_e32 v187, 0xffff0000, v182
	v_pk_fma_f32 v[220:221], v[220:221], v[184:185], v[186:187]
	v_lshlrev_b32_e32 v184, 16, v151
	v_and_b32_e32 v185, 0xffff0000, v151
	v_lshlrev_b32_e32 v186, 16, v183
	v_and_b32_e32 v187, 0xffff0000, v183
	v_pk_fma_f32 v[222:223], v[222:223], v[184:185], v[186:187]
	v_cvt_pk_bf16_f32 v148, v244, v245
	v_cvt_pk_bf16_f32 v149, v246, v247
	v_cvt_pk_bf16_f32 v150, v220, v221
	v_cvt_pk_bf16_f32 v151, v222, v223
	v_add_u32_e32 v219, 0x5000, v218
	global_store_dwordx4 v219, v[148:151], s[22:23]
	v_add_u32_e32 v219, 12, v212
	v_and_b32_e32 v219, 7, v219
	v_xor_b32_e32 v219, v213, v219
	v_add_u32_e32 v228, 12, v215
	v_lshlrev_b32_e32 v228, 10, v228
	v_lshl_add_u32 v228, v219, 4, v228
	v_xor_b32_e32 v229, 16, v228
	ds_read_b128 v[244:247], v228
	ds_read_b128 v[220:223], v229
	s_waitcnt vmcnt(8)
	s_waitcnt lgkmcnt(0)
; #define EPI_FOR(u) \
;     _Pragma("unroll") for (int ai = 0; ai < 2; ++ai) _Pragma("unroll") for (int m = 0; m < 4; ++m) _Pragma("unroll") for (int bj = 0; bj < 2; ++bj)
; #define EPI_COL(u) (EPI_CB(u) + 8 * fq)
; DI u32x4 pack8(const float* v) { u32x4 w; w.x = pk2(v[0], v[1]); w.y = pk2(v[2], v[3]); w.z = pk2(v[4], v[5]); w.w = pk2(v[6], v[7]); return w; }
;     DI void operator()(const Acc& acc, const Unit& u, int wr, int wc, int fr, int fq) const {
;         EPI_FOR(u) {
;             const int row = EPI_ROW(u), col = EPI_COL(u); EPI_V(v);
;             const u32x4 gg = *(const u32x4*)(gate + (size_t)row * 3072 + gi * 1024 + col);
;             const float gf[8] = {bflo(gg.x), bfhi(gg.x), bflo(gg.y), bfhi(gg.y), bflo(gg.z), bfhi(gg.z), bflo(gg.w), bfhi(gg.w)};
;             bf16_t* mp = mrg + (size_t)row * 1024 + col;
;             if (accum) {
;                 const u32x4 oo = *(const u32x4*)mp;
;                 const float of[8] = {bflo(oo.x), bfhi(oo.x), bflo(oo.y), bfhi(oo.y), bflo(oo.z), bfhi(oo.z), bflo(oo.w), bfhi(oo.w)};
; #pragma unroll
;                 for (int j = 0; j < 8; ++j) v[j] = of[j] + gf[j] * v[j];
;             } else {
; #pragma unroll
;                 for (int j = 0; j < 8; ++j) v[j] = gf[j] * v[j];
;             }
;             *(u32x4*)mp = pack8(v);
;         }
	v_lshlrev_b32_e32 v184, 16, v152
	v_and_b32_e32 v185, 0xffff0000, v152
	v_lshlrev_b32_e32 v186, 16, v224
	v_and_b32_e32 v187, 0xffff0000, v224
	v_pk_fma_f32 v[244:245], v[244:245], v[184:185], v[186:187]
	v_lshlrev_b32_e32 v184, 16, v153
	v_and_b32_e32 v185, 0xffff0000, v153
	v_lshlrev_b32_e32 v186, 16, v225
	v_and_b32_e32 v187, 0xffff0000, v225
	v_pk_fma_f32 v[246:247], v[246:247], v[184:185], v[186:187]
	v_lshlrev_b32_e32 v184, 16, v154
	v_and_b32_e32 v185, 0xffff0000, v154
	v_lshlrev_b32_e32 v186, 16, v226
	v_and_b32_e32 v187, 0xffff0000, v226
	v_pk_fma_f32 v[220:221], v[220:221], v[184:185], v[186:187]
	v_lshlrev_b32_e32 v184, 16, v155
	v_and_b32_e32 v185, 0xffff0000, v155
	v_lshlrev_b32_e32 v186, 16, v227
	v_and_b32_e32 v187, 0xffff0000, v227
	v_pk_fma_f32 v[222:223], v[222:223], v[184:185], v[186:187]
	v_cvt_pk_bf16_f32 v152, v244, v245
	v_cvt_pk_bf16_f32 v153, v246, v247
	v_cvt_pk_bf16_f32 v154, v220, v221
	v_cvt_pk_bf16_f32 v155, v222, v223
	v_add_u32_e32 v219, 0x6000, v218
	global_store_dwordx4 v219, v[152:155], s[22:23]
	v_add_u32_e32 v219, 14, v212
	v_and_b32_e32 v219, 7, v219
	v_xor_b32_e32 v219, v213, v219
	v_add_u32_e32 v228, 14, v215
	v_lshlrev_b32_e32 v228, 10, v228
	v_lshl_add_u32 v228, v219, 4, v228
	v_xor_b32_e32 v229, 16, v228
	ds_read_b128 v[244:247], v228
	ds_read_b128 v[220:223], v229
	s_waitcnt vmcnt(7)
	s_waitcnt lgkmcnt(0)
	v_lshlrev_b32_e32 v184, 16, v156
	v_and_b32_e32 v185, 0xffff0000, v156
	v_lshlrev_b32_e32 v186, 16, v240
	v_and_b32_e32 v187, 0xffff0000, v240
	v_pk_fma_f32 v[244:245], v[244:245], v[184:185], v[186:187]
	v_lshlrev_b32_e32 v184, 16, v157
	v_and_b32_e32 v185, 0xffff0000, v157
	v_lshlrev_b32_e32 v186, 16, v241
	v_and_b32_e32 v187, 0xffff0000, v241
	v_pk_fma_f32 v[246:247], v[246:247], v[184:185], v[186:187]
	v_lshlrev_b32_e32 v184, 16, v158
	v_and_b32_e32 v185, 0xffff0000, v158
	v_lshlrev_b32_e32 v186, 16, v242
	v_and_b32_e32 v187, 0xffff0000, v242
	v_pk_fma_f32 v[220:221], v[220:221], v[184:185], v[186:187]
	v_lshlrev_b32_e32 v184, 16, v159
	v_and_b32_e32 v185, 0xffff0000, v159
	v_lshlrev_b32_e32 v186, 16, v243
	v_and_b32_e32 v187, 0xffff0000, v243
	v_pk_fma_f32 v[222:223], v[222:223], v[184:185], v[186:187]
	v_cvt_pk_bf16_f32 v156, v244, v245
	v_cvt_pk_bf16_f32 v157, v246, v247
	v_cvt_pk_bf16_f32 v158, v220, v221
	v_cvt_pk_bf16_f32 v159, v222, v223
	v_add_u32_e32 v219, 0x7000, v218
	global_store_dwordx4 v219, v[156:159], s[22:23]
	s_barrier
	ds_write_b128 v210, v[60:63]
	ds_write_b128 v211, v[56:59]
	ds_write_b128 v210, v[52:55] offset:512
	ds_write_b128 v211, v[48:51] offset:512
	ds_write_b128 v210, v[44:47] offset:16384
	ds_write_b128 v211, v[40:43] offset:16384
	ds_write_b128 v210, v[36:39] offset:16896
	ds_write_b128 v211, v[32:35] offset:16896
	ds_write_b128 v210, v[28:31] offset:32768
	ds_write_b128 v211, v[24:27] offset:32768
	ds_write_b128 v210, v[20:23] offset:33280
	ds_write_b128 v211, v[16:19] offset:33280
	ds_write_b128 v210, v[12:15] offset:49152
	ds_write_b128 v211, v[8:11] offset:49152
	ds_write_b128 v210, v[4:7] offset:49664
	ds_write_b128 v211, v[0:3] offset:49664
	s_waitcnt lgkmcnt(0)
	s_barrier
	v_add_u32_e32 v215, s7, v212
	s_add_i32 s8, s2, 128
	v_add_u32_e32 v216, s8, v215
	v_mul_u32_u24_e32 v217, 0x1800, v216
	v_add_u32_e32 v217, v217, v214
	v_add_u32_e32 v217, 0x1000, v217
	v_lshl_add_u32 v218, v216, 11, v214
	global_load_dwordx4 v[128:131], v217, s[20:21]
	global_load_dwordx4 v[160:163], v218, s[22:23]
	v_add_u32_e32 v219, 0x3000, v217
	global_load_dwordx4 v[132:135], v219, s[20:21]
	v_add_u32_e32 v219, 0x1000, v218
	global_load_dwordx4 v[164:167], v219, s[22:23]
	v_add_u32_e32 v219, 0x6000, v217
	global_load_dwordx4 v[136:139], v219, s[20:21]
	v_add_u32_e32 v219, 0x2000, v218
	global_load_dwordx4 v[168:171], v219, s[22:23]
	v_add_u32_e32 v219, 0x9000, v217
	global_load_dwordx4 v[140:143], v219, s[20:21]
	v_add_u32_e32 v219, 0x3000, v218
	global_load_dwordx4 v[172:175], v219, s[22:23]
	v_add_u32_e32 v219, 0xc000, v217
	global_load_dwordx4 v[144:147], v219, s[20:21]
	v_add_u32_e32 v219, 0x4000, v218
	global_load_dwordx4 v[176:179], v219, s[22:23]
	v_add_u32_e32 v219, 0xf000, v217
	global_load_dwordx4 v[148:151], v219, s[20:21]
	v_add_u32_e32 v219, 0x5000, v218
	global_load_dwordx4 v[180:183], v219, s[22:23]
	v_add_u32_e32 v219, 0x12000, v217
	global_load_dwordx4 v[152:155], v219, s[20:21]
	v_add_u32_e32 v219, 0x6000, v218
	global_load_dwordx4 v[224:227], v219, s[22:23]
	v_add_u32_e32 v219, 0x15000, v217
	global_load_dwordx4 v[156:159], v219, s[20:21]
	v_add_u32_e32 v219, 0x7000, v218
	global_load_dwordx4 v[240:243], v219, s[22:23]
	v_add_u32_e32 v219, 0, v212
	v_and_b32_e32 v219, 7, v219
	v_xor_b32_e32 v219, v213, v219
	v_add_u32_e32 v228, 0, v215
	v_lshlrev_b32_e32 v228, 10, v228
	v_lshl_add_u32 v228, v219, 4, v228
	v_xor_b32_e32 v229, 16, v228
	ds_read_b128 v[244:247], v228
	ds_read_b128 v[220:223], v229
	s_waitcnt vmcnt(14)
	s_waitcnt lgkmcnt(0)
	v_lshlrev_b32_e32 v184, 16, v128
	v_and_b32_e32 v185, 0xffff0000, v128
	v_lshlrev_b32_e32 v186, 16, v160
	v_and_b32_e32 v187, 0xffff0000, v160
	v_pk_fma_f32 v[244:245], v[244:245], v[184:185], v[186:187]
	v_lshlrev_b32_e32 v184, 16, v129
	v_and_b32_e32 v185, 0xffff0000, v129
	v_lshlrev_b32_e32 v186, 16, v161
	v_and_b32_e32 v187, 0xffff0000, v161
	v_pk_fma_f32 v[246:247], v[246:247], v[184:185], v[186:187]
	v_lshlrev_b32_e32 v184, 16, v130
	v_and_b32_e32 v185, 0xffff0000, v130
	v_lshlrev_b32_e32 v186, 16, v162
	v_and_b32_e32 v187, 0xffff0000, v162
	v_pk_fma_f32 v[220:221], v[220:221], v[184:185], v[186:187]
	v_lshlrev_b32_e32 v184, 16, v131
	v_and_b32_e32 v185, 0xffff0000, v131
	v_lshlrev_b32_e32 v186, 16, v163
	v_and_b32_e32 v187, 0xffff0000, v163
	v_pk_fma_f32 v[222:223], v[222:223], v[184:185], v[186:187]
	v_cvt_pk_bf16_f32 v128, v244, v245
	v_cvt_pk_bf16_f32 v129, v246, v247
	v_cvt_pk_bf16_f32 v130, v220, v221
	v_cvt_pk_bf16_f32 v131, v222, v223
	global_store_dwordx4 v218, v[128:131], s[22:23]
	v_add_u32_e32 v219, 2, v212
	v_and_b32_e32 v219, 7, v219
	v_xor_b32_e32 v219, v213, v219
	v_add_u32_e32 v228, 2, v215
	v_lshlrev_b32_e32 v228, 10, v228
	v_lshl_add_u32 v228, v219, 4, v228
	v_xor_b32_e32 v229, 16, v228
	ds_read_b128 v[244:247], v228
	ds_read_b128 v[220:223], v229
	s_waitcnt vmcnt(13)
; #define EPI_FOR(u) \
;     _Pragma("unroll") for (int ai = 0; ai < 2; ++ai) _Pragma("unroll") for (int m = 0; m < 4; ++m) _Pragma("unroll") for (int bj = 0; bj < 2; ++bj)
; #define EPI_COL(u) (EPI_CB(u) + 8 * fq)
; DI u32x4 pack8(const float* v) { u32x4 w; w.x = pk2(v[0], v[1]); w.y = pk2(v[2], v[3]); w.z = pk2(v[4], v[5]); w.w = pk2(v[6], v[7]); return w; }
;     DI void operator()(const Acc& acc, const Unit& u, int wr, int wc, int fr, int fq) const {
;         EPI_FOR(u) {
;             const int row = EPI_ROW(u), col = EPI_COL(u); EPI_V(v);
;             const u32x4 gg = *(const u32x4*)(gate + (size_t)row * 3072 + gi * 1024 + col);
;             const float gf[8] = {bflo(gg.x), bfhi(gg.x), bflo(gg.y), bfhi(gg.y), bflo(gg.z), bfhi(gg.z), bflo(gg.w), bfhi(gg.w)};
;             bf16_t* mp = mrg + (size_t)row * 1024 + col;
;             if (accum) {
;                 const u32x4 oo = *(const u32x4*)mp;
;                 const float of[8] = {bflo(oo.x), bfhi(oo.x), bflo(oo.y), bfhi(oo.y), bflo(oo.z), bfhi(oo.z), bflo(oo.w), bfhi(oo.w)};
; #pragma unroll
;                 for (int j = 0; j < 8; ++j) v[j] = of[j] + gf[j] * v[j];
;             } else {
; #pragma unroll
;                 for (int j = 0; j < 8; ++j) v[j] = gf[j] * v[j];
;             }
;             *(u32x4*)mp = pack8(v);
;         }
	s_waitcnt lgkmcnt(0)
	v_lshlrev_b32_e32 v184, 16, v132
	v_and_b32_e32 v185, 0xffff0000, v132
	v_lshlrev_b32_e32 v186, 16, v164
	v_and_b32_e32 v187, 0xffff0000, v164
	v_pk_fma_f32 v[244:245], v[244:245], v[184:185], v[186:187]
	v_lshlrev_b32_e32 v184, 16, v133
	v_and_b32_e32 v185, 0xffff0000, v133
	v_lshlrev_b32_e32 v186, 16, v165
	v_and_b32_e32 v187, 0xffff0000, v165
	v_pk_fma_f32 v[246:247], v[246:247], v[184:185], v[186:187]
	v_lshlrev_b32_e32 v184, 16, v134
	v_and_b32_e32 v185, 0xffff0000, v134
	v_lshlrev_b32_e32 v186, 16, v166
	v_and_b32_e32 v187, 0xffff0000, v166
	v_pk_fma_f32 v[220:221], v[220:221], v[184:185], v[186:187]
	v_lshlrev_b32_e32 v184, 16, v135
	v_and_b32_e32 v185, 0xffff0000, v135
	v_lshlrev_b32_e32 v186, 16, v167
	v_and_b32_e32 v187, 0xffff0000, v167
	v_pk_fma_f32 v[222:223], v[222:223], v[184:185], v[186:187]
	v_cvt_pk_bf16_f32 v132, v244, v245
	v_cvt_pk_bf16_f32 v133, v246, v247
	v_cvt_pk_bf16_f32 v134, v220, v221
	v_cvt_pk_bf16_f32 v135, v222, v223
	v_add_u32_e32 v219, 0x1000, v218
	global_store_dwordx4 v219, v[132:135], s[22:23]
	v_add_u32_e32 v219, 4, v212
	v_and_b32_e32 v219, 7, v219
	v_xor_b32_e32 v219, v213, v219
	v_add_u32_e32 v228, 4, v215
	v_lshlrev_b32_e32 v228, 10, v228
	v_lshl_add_u32 v228, v219, 4, v228
	v_xor_b32_e32 v229, 16, v228
	ds_read_b128 v[244:247], v228
	ds_read_b128 v[220:223], v229
	s_waitcnt vmcnt(12)
	s_waitcnt lgkmcnt(0)
	v_lshlrev_b32_e32 v184, 16, v136
	v_and_b32_e32 v185, 0xffff0000, v136
	v_lshlrev_b32_e32 v186, 16, v168
	v_and_b32_e32 v187, 0xffff0000, v168
	v_pk_fma_f32 v[244:245], v[244:245], v[184:185], v[186:187]
	v_lshlrev_b32_e32 v184, 16, v137
	v_and_b32_e32 v185, 0xffff0000, v137
	v_lshlrev_b32_e32 v186, 16, v169
	v_and_b32_e32 v187, 0xffff0000, v169
	v_pk_fma_f32 v[246:247], v[246:247], v[184:185], v[186:187]
	v_lshlrev_b32_e32 v184, 16, v138
	v_and_b32_e32 v185, 0xffff0000, v138
	v_lshlrev_b32_e32 v186, 16, v170
	v_and_b32_e32 v187, 0xffff0000, v170
	v_pk_fma_f32 v[220:221], v[220:221], v[184:185], v[186:187]
	v_lshlrev_b32_e32 v184, 16, v139
	v_and_b32_e32 v185, 0xffff0000, v139
	v_lshlrev_b32_e32 v186, 16, v171
	v_and_b32_e32 v187, 0xffff0000, v171
	v_pk_fma_f32 v[222:223], v[222:223], v[184:185], v[186:187]
	v_cvt_pk_bf16_f32 v136, v244, v245
	v_cvt_pk_bf16_f32 v137, v246, v247
	v_cvt_pk_bf16_f32 v138, v220, v221
	v_cvt_pk_bf16_f32 v139, v222, v223
	v_add_u32_e32 v219, 0x2000, v218
	global_store_dwordx4 v219, v[136:139], s[22:23]
	v_add_u32_e32 v219, 6, v212
	v_and_b32_e32 v219, 7, v219
	v_xor_b32_e32 v219, v213, v219
	v_add_u32_e32 v228, 6, v215
	v_lshlrev_b32_e32 v228, 10, v228
	v_lshl_add_u32 v228, v219, 4, v228
	v_xor_b32_e32 v229, 16, v228
	ds_read_b128 v[244:247], v228
	ds_read_b128 v[220:223], v229
	s_waitcnt vmcnt(11)
	s_waitcnt lgkmcnt(0)
	v_lshlrev_b32_e32 v184, 16, v140
	v_and_b32_e32 v185, 0xffff0000, v140
	v_lshlrev_b32_e32 v186, 16, v172
	v_and_b32_e32 v187, 0xffff0000, v172
	v_pk_fma_f32 v[244:245], v[244:245], v[184:185], v[186:187]
	v_lshlrev_b32_e32 v184, 16, v141
	v_and_b32_e32 v185, 0xffff0000, v141
	v_lshlrev_b32_e32 v186, 16, v173
	v_and_b32_e32 v187, 0xffff0000, v173
	v_pk_fma_f32 v[246:247], v[246:247], v[184:185], v[186:187]
	v_lshlrev_b32_e32 v184, 16, v142
	v_and_b32_e32 v185, 0xffff0000, v142
	v_lshlrev_b32_e32 v186, 16, v174
	v_and_b32_e32 v187, 0xffff0000, v174
	v_pk_fma_f32 v[220:221], v[220:221], v[184:185], v[186:187]
	v_lshlrev_b32_e32 v184, 16, v143
	v_and_b32_e32 v185, 0xffff0000, v143
	v_lshlrev_b32_e32 v186, 16, v175
	v_and_b32_e32 v187, 0xffff0000, v175
	v_pk_fma_f32 v[222:223], v[222:223], v[184:185], v[186:187]
	v_cvt_pk_bf16_f32 v140, v244, v245
	v_cvt_pk_bf16_f32 v141, v246, v247
	v_cvt_pk_bf16_f32 v142, v220, v221
	v_cvt_pk_bf16_f32 v143, v222, v223
	v_add_u32_e32 v219, 0x3000, v218
	global_store_dwordx4 v219, v[140:143], s[22:23]
	v_add_u32_e32 v219, 8, v212
	v_and_b32_e32 v219, 7, v219
	v_xor_b32_e32 v219, v213, v219
	v_add_u32_e32 v228, 8, v215
	v_lshlrev_b32_e32 v228, 10, v228
	v_lshl_add_u32 v228, v219, 4, v228
	v_xor_b32_e32 v229, 16, v228
	ds_read_b128 v[244:247], v228
	ds_read_b128 v[220:223], v229
	s_waitcnt vmcnt(10)
	s_waitcnt lgkmcnt(0)
; #define PG8_BAR __builtin_amdgcn_s_barrier()
; #define EPI_FOR(u) \
;     _Pragma("unroll") for (int ai = 0; ai < 2; ++ai) _Pragma("unroll") for (int m = 0; m < 4; ++m) _Pragma("unroll") for (int bj = 0; bj < 2; ++bj)
; #define EPI_COL(u) (EPI_CB(u) + 8 * fq)
; DI u32x4 pack8(const float* v) { u32x4 w; w.x = pk2(v[0], v[1]); w.y = pk2(v[2], v[3]); w.z = pk2(v[4], v[5]); w.w = pk2(v[6], v[7]); return w; }
; template <class Epi>
; DI void gemm_phase(LAS unsigned char* lds, const Gemm g, const Sched& S, const Epi& E) {
;     ...
;         if (!has_next) break;
; #pragma unroll
;         for (int a = 0; a < 2; ++a)
; #pragma unroll
;             for (int b = 0; b < 2; ++b)
; #pragma unroll
;                 for (int m = 0; m < 4; ++m)
; #pragma unroll
;                     for (int n = 0; n < 2; ++n) acc[a][b][m][n] = (f32x4){0.f, 0.f, 0.f, 0.f};
;         cur = nxt; cA = nA; cB = nB; ++ui;
;         if (wr == 1) PG8_BAR;
;     DI void operator()(const Acc& acc, const Unit& u, int wr, int wc, int fr, int fq) const {
;         EPI_FOR(u) {
;             const int row = EPI_ROW(u), col = EPI_COL(u); EPI_V(v);
;             const u32x4 gg = *(const u32x4*)(gate + (size_t)row * 3072 + gi * 1024 + col);
;             const float gf[8] = {bflo(gg.x), bfhi(gg.x), bflo(gg.y), bfhi(gg.y), bflo(gg.z), bfhi(gg.z), bflo(gg.w), bfhi(gg.w)};
;             bf16_t* mp = mrg + (size_t)row * 1024 + col;
;             if (accum) {
;                 const u32x4 oo = *(const u32x4*)mp;
;                 const float of[8] = {bflo(oo.x), bfhi(oo.x), bflo(oo.y), bfhi(oo.y), bflo(oo.z), bfhi(oo.z), bflo(oo.w), bfhi(oo.w)};
; #pragma unroll
;                 for (int j = 0; j < 8; ++j) v[j] = of[j] + gf[j] * v[j];
;             } else {
; #pragma unroll
;                 for (int j = 0; j < 8; ++j) v[j] = gf[j] * v[j];
;             }
;             *(u32x4*)mp = pack8(v);
;         }
	v_lshlrev_b32_e32 v184, 16, v144
	v_and_b32_e32 v185, 0xffff0000, v144
	v_lshlrev_b32_e32 v186, 16, v176
	v_and_b32_e32 v187, 0xffff0000, v176
	v_pk_fma_f32 v[244:245], v[244:245], v[184:185], v[186:187]
	v_lshlrev_b32_e32 v184, 16, v145
	v_and_b32_e32 v185, 0xffff0000, v145
	v_lshlrev_b32_e32 v186, 16, v177
	v_and_b32_e32 v187, 0xffff0000, v177
	v_pk_fma_f32 v[246:247], v[246:247], v[184:185], v[186:187]
	v_lshlrev_b32_e32 v184, 16, v146
	v_and_b32_e32 v185, 0xffff0000, v146
	v_lshlrev_b32_e32 v186, 16, v178
	v_and_b32_e32 v187, 0xffff0000, v178
	v_pk_fma_f32 v[220:221], v[220:221], v[184:185], v[186:187]
	v_lshlrev_b32_e32 v184, 16, v147
	v_and_b32_e32 v185, 0xffff0000, v147
	v_lshlrev_b32_e32 v186, 16, v179
	v_and_b32_e32 v187, 0xffff0000, v179
	v_pk_fma_f32 v[222:223], v[222:223], v[184:185], v[186:187]
	v_cvt_pk_bf16_f32 v144, v244, v245
	v_cvt_pk_bf16_f32 v145, v246, v247
	v_cvt_pk_bf16_f32 v146, v220, v221
	v_cvt_pk_bf16_f32 v147, v222, v223
	v_add_u32_e32 v219, 0x4000, v218
	global_store_dwordx4 v219, v[144:147], s[22:23]
	v_add_u32_e32 v219, 10, v212
	v_and_b32_e32 v219, 7, v219
	v_xor_b32_e32 v219, v213, v219
	v_add_u32_e32 v228, 10, v215
	v_lshlrev_b32_e32 v228, 10, v228
	v_lshl_add_u32 v228, v219, 4, v228
	v_xor_b32_e32 v229, 16, v228
	ds_read_b128 v[244:247], v228
	ds_read_b128 v[220:223], v229
	s_waitcnt vmcnt(9)
	s_waitcnt lgkmcnt(0)
	v_lshlrev_b32_e32 v184, 16, v148
	v_and_b32_e32 v185, 0xffff0000, v148
	v_lshlrev_b32_e32 v186, 16, v180
	v_and_b32_e32 v187, 0xffff0000, v180
	v_pk_fma_f32 v[244:245], v[244:245], v[184:185], v[186:187]
	v_lshlrev_b32_e32 v184, 16, v149
	v_and_b32_e32 v185, 0xffff0000, v149
	v_lshlrev_b32_e32 v186, 16, v181
	v_and_b32_e32 v187, 0xffff0000, v181
	v_pk_fma_f32 v[246:247], v[246:247], v[184:185], v[186:187]
	v_lshlrev_b32_e32 v184, 16, v150
	v_and_b32_e32 v185, 0xffff0000, v150
	v_lshlrev_b32_e32 v186, 16, v182
	v_and_b32_e32 v187, 0xffff0000, v182
	v_pk_fma_f32 v[220:221], v[220:221], v[184:185], v[186:187]
	v_lshlrev_b32_e32 v184, 16, v151
	v_and_b32_e32 v185, 0xffff0000, v151
	v_lshlrev_b32_e32 v186, 16, v183
	v_and_b32_e32 v187, 0xffff0000, v183
	v_pk_fma_f32 v[222:223], v[222:223], v[184:185], v[186:187]
	v_cvt_pk_bf16_f32 v148, v244, v245
	v_cvt_pk_bf16_f32 v149, v246, v247
	v_cvt_pk_bf16_f32 v150, v220, v221
	v_cvt_pk_bf16_f32 v151, v222, v223
	v_add_u32_e32 v219, 0x5000, v218
	global_store_dwordx4 v219, v[148:151], s[22:23]
	v_add_u32_e32 v219, 12, v212
	v_and_b32_e32 v219, 7, v219
	v_xor_b32_e32 v219, v213, v219
	v_add_u32_e32 v228, 12, v215
	v_lshlrev_b32_e32 v228, 10, v228
	v_lshl_add_u32 v228, v219, 4, v228
	v_xor_b32_e32 v229, 16, v228
	ds_read_b128 v[244:247], v228
	ds_read_b128 v[220:223], v229
	s_waitcnt vmcnt(8)
	s_waitcnt lgkmcnt(0)
	v_lshlrev_b32_e32 v184, 16, v152
	v_and_b32_e32 v185, 0xffff0000, v152
	v_lshlrev_b32_e32 v186, 16, v224
	v_and_b32_e32 v187, 0xffff0000, v224
	v_pk_fma_f32 v[244:245], v[244:245], v[184:185], v[186:187]
	v_lshlrev_b32_e32 v184, 16, v153
	v_and_b32_e32 v185, 0xffff0000, v153
	v_lshlrev_b32_e32 v186, 16, v225
	v_and_b32_e32 v187, 0xffff0000, v225
	v_pk_fma_f32 v[246:247], v[246:247], v[184:185], v[186:187]
	v_lshlrev_b32_e32 v184, 16, v154
	v_and_b32_e32 v185, 0xffff0000, v154
	v_lshlrev_b32_e32 v186, 16, v226
	v_and_b32_e32 v187, 0xffff0000, v226
	v_pk_fma_f32 v[220:221], v[220:221], v[184:185], v[186:187]
	v_lshlrev_b32_e32 v184, 16, v155
	v_and_b32_e32 v185, 0xffff0000, v155
	v_lshlrev_b32_e32 v186, 16, v227
	v_and_b32_e32 v187, 0xffff0000, v227
	v_pk_fma_f32 v[222:223], v[222:223], v[184:185], v[186:187]
	v_cvt_pk_bf16_f32 v152, v244, v245
	v_cvt_pk_bf16_f32 v153, v246, v247
	v_cvt_pk_bf16_f32 v154, v220, v221
	v_cvt_pk_bf16_f32 v155, v222, v223
	v_add_u32_e32 v219, 0x6000, v218
	global_store_dwordx4 v219, v[152:155], s[22:23]
	v_add_u32_e32 v219, 14, v212
	v_and_b32_e32 v219, 7, v219
	v_xor_b32_e32 v219, v213, v219
	v_add_u32_e32 v228, 14, v215
	v_lshlrev_b32_e32 v228, 10, v228
	v_lshl_add_u32 v228, v219, 4, v228
	v_xor_b32_e32 v229, 16, v228
	ds_read_b128 v[244:247], v228
	ds_read_b128 v[220:223], v229
	s_waitcnt vmcnt(7)
	s_waitcnt lgkmcnt(0)
	v_lshlrev_b32_e32 v184, 16, v156
	v_and_b32_e32 v185, 0xffff0000, v156
	v_lshlrev_b32_e32 v186, 16, v240
	v_and_b32_e32 v187, 0xffff0000, v240
	v_pk_fma_f32 v[244:245], v[244:245], v[184:185], v[186:187]
	v_lshlrev_b32_e32 v184, 16, v157
	v_and_b32_e32 v185, 0xffff0000, v157
	v_lshlrev_b32_e32 v186, 16, v241
	v_and_b32_e32 v187, 0xffff0000, v241
	v_pk_fma_f32 v[246:247], v[246:247], v[184:185], v[186:187]
	v_lshlrev_b32_e32 v184, 16, v158
	v_and_b32_e32 v185, 0xffff0000, v158
	v_lshlrev_b32_e32 v186, 16, v242
	v_and_b32_e32 v187, 0xffff0000, v242
	v_pk_fma_f32 v[220:221], v[220:221], v[184:185], v[186:187]
	v_lshlrev_b32_e32 v184, 16, v159
	v_and_b32_e32 v185, 0xffff0000, v159
	v_lshlrev_b32_e32 v186, 16, v243
	v_and_b32_e32 v187, 0xffff0000, v243
	v_pk_fma_f32 v[222:223], v[222:223], v[184:185], v[186:187]
	v_cvt_pk_bf16_f32 v156, v244, v245
	v_cvt_pk_bf16_f32 v157, v246, v247
	v_cvt_pk_bf16_f32 v158, v220, v221
	v_cvt_pk_bf16_f32 v159, v222, v223
	v_add_u32_e32 v219, 0x7000, v218
	global_store_dwordx4 v219, v[156:159], s[22:23]
	s_mov_b32 s61, 0xc000
	s_mov_b32 s60, 0x39800000
	s_mov_b64 s[8:9], 0x1000
	s_mov_b64 s[6:7], -1
	s_andn2_b64 vcc, exec, s[14:15]
	s_cbranch_vccnz .LBB0_1211
	s_andn2_b64 vcc, exec, s[16:17]
	s_cbranch_vccnz .LBB0_1210
	s_barrier
	s_branch .LBB0_1210

; #define EPI_FOR(u) \
;     _Pragma("unroll") for (int ai = 0; ai < 2; ++ai) _Pragma("unroll") for (int m = 0; m < 4; ++m) _Pragma("unroll") for (int bj = 0; bj < 2; ++bj)
; #define EPI_COL(u) (EPI_CB(u) + 8 * fq)
; DI u32x4 pack8(const float* v) { u32x4 w; w.x = pk2(v[0], v[1]); w.y = pk2(v[2], v[3]); w.z = pk2(v[4], v[5]); w.w = pk2(v[6], v[7]); return w; }
;     DI void operator()(const Acc& acc, const Unit& u, int wr, int wc, int fr, int fq) const {
;         EPI_FOR(u) {
;             const int row = EPI_ROW(u), col = EPI_COL(u); EPI_V(v);
;             const u32x4 gg = *(const u32x4*)(gate + (size_t)row * 3072 + gi * 1024 + col);
;             const float gf[8] = {bflo(gg.x), bfhi(gg.x), bflo(gg.y), bfhi(gg.y), bflo(gg.z), bfhi(gg.z), bflo(gg.w), bfhi(gg.w)};
;             bf16_t* mp = mrg + (size_t)row * 1024 + col;
;             if (accum) {
;                 const u32x4 oo = *(const u32x4*)mp;
;                 const float of[8] = {bflo(oo.x), bfhi(oo.x), bflo(oo.y), bfhi(oo.y), bflo(oo.z), bfhi(oo.z), bflo(oo.w), bfhi(oo.w)};
; #pragma unroll
;                 for (int j = 0; j < 8; ++j) v[j] = of[j] + gf[j] * v[j];
;             } else {
; #pragma unroll
;                 for (int j = 0; j < 8; ++j) v[j] = gf[j] * v[j];
;             }
;             *(u32x4*)mp = pack8(v);
;         }
.LBB0_1248:
	s_lshl_b32 s2, s28, 8
	s_lshl_b32 s6, s29, 8
	v_readfirstlane_b32 s7, v232
	s_lshr_b32 s7, s7, 6
	s_lshl_b32 s7, s7, 4
	v_add_u32_e32 v210, s51, v145
	v_lshlrev_b32_e32 v210, 10, v210
	v_and_b32_e32 v211, 7, v145
	v_lshlrev_b32_e32 v212, 1, v144
	v_xor_b32_e32 v211, v212, v211
	v_lshl_add_u32 v210, v211, 4, v210
	s_lshl_b32 s8, s54, 2
	v_add_u32_e32 v210, s8, v210
	v_xor_b32_e32 v211, 16, v210
	v_lshrrev_b32_e32 v212, 5, v233
	v_and_b32_e32 v213, 31, v233
	v_lshl_add_u32 v214, v213, 3, s6
	v_lshlrev_b32_e32 v214, 1, v214
	v_lshlrev_b32_e32 v213, 1, v213
	s_waitcnt vmcnt(0)
	s_barrier
	ds_write_b128 v210, v[124:127]
	ds_write_b128 v211, v[120:123]
	ds_write_b128 v210, v[116:119] offset:512
	ds_write_b128 v211, v[112:115] offset:512
	ds_write_b128 v210, v[108:111] offset:16384
	ds_write_b128 v211, v[104:107] offset:16384
	ds_write_b128 v210, v[100:103] offset:16896
	ds_write_b128 v211, v[96:99] offset:16896
	ds_write_b128 v210, v[92:95] offset:32768
	ds_write_b128 v211, v[88:91] offset:32768
	ds_write_b128 v210, v[84:87] offset:33280
	ds_write_b128 v211, v[80:83] offset:33280
	ds_write_b128 v210, v[76:79] offset:49152
	ds_write_b128 v211, v[72:75] offset:49152
	ds_write_b128 v210, v[68:71] offset:49664
	ds_write_b128 v211, v[64:67] offset:49664
	s_waitcnt lgkmcnt(0)
	s_barrier
	v_add_u32_e32 v215, s7, v212
	s_add_i32 s8, s2, 0
	v_add_u32_e32 v216, s8, v215
	v_mul_u32_u24_e32 v217, 0x1800, v216
	v_add_u32_e32 v217, v217, v214
	v_add_u32_e32 v217, 0x800, v217
	v_lshl_add_u32 v218, v216, 11, v214
	global_load_dwordx4 v[128:131], v217, s[22:23]
	global_load_dwordx4 v[160:163], v218, s[24:25]
	v_add_u32_e32 v219, 0x3000, v217
	global_load_dwordx4 v[132:135], v219, s[22:23]
	v_add_u32_e32 v219, 0x1000, v218
	global_load_dwordx4 v[164:167], v219, s[24:25]
	v_add_u32_e32 v219, 0x6000, v217
	global_load_dwordx4 v[136:139], v219, s[22:23]
	v_add_u32_e32 v219, 0x2000, v218
	global_load_dwordx4 v[168:171], v219, s[24:25]
	v_add_u32_e32 v219, 0x9000, v217
	global_load_dwordx4 v[140:143], v219, s[22:23]
	v_add_u32_e32 v219, 0x3000, v218
	global_load_dwordx4 v[172:175], v219, s[24:25]
	v_add_u32_e32 v219, 0xc000, v217
	global_load_dwordx4 v[144:147], v219, s[22:23]
	v_add_u32_e32 v219, 0x4000, v218
	global_load_dwordx4 v[176:179], v219, s[24:25]
	v_add_u32_e32 v219, 0xf000, v217
	global_load_dwordx4 v[148:151], v219, s[22:23]
	v_add_u32_e32 v219, 0x5000, v218
	global_load_dwordx4 v[180:183], v219, s[24:25]
	v_add_u32_e32 v219, 0x12000, v217
	global_load_dwordx4 v[152:155], v219, s[22:23]
	v_add_u32_e32 v219, 0x6000, v218
	global_load_dwordx4 v[224:227], v219, s[24:25]
	v_add_u32_e32 v219, 0x15000, v217
	global_load_dwordx4 v[156:159], v219, s[22:23]
	v_add_u32_e32 v219, 0x7000, v218
	global_load_dwordx4 v[240:243], v219, s[24:25]
	v_add_u32_e32 v219, 0, v212
	v_and_b32_e32 v219, 7, v219
	v_xor_b32_e32 v219, v213, v219
	v_add_u32_e32 v228, 0, v215
	v_lshlrev_b32_e32 v228, 10, v228
	v_lshl_add_u32 v228, v219, 4, v228
	v_xor_b32_e32 v229, 16, v228
	ds_read_b128 v[244:247], v228
	ds_read_b128 v[220:223], v229
	s_waitcnt vmcnt(14)
	s_waitcnt lgkmcnt(0)
	v_lshlrev_b32_e32 v184, 16, v128
	v_and_b32_e32 v185, 0xffff0000, v128
	v_lshlrev_b32_e32 v186, 16, v160
	v_and_b32_e32 v187, 0xffff0000, v160
	v_pk_fma_f32 v[244:245], v[244:245], v[184:185], v[186:187]
	v_lshlrev_b32_e32 v184, 16, v129
	v_and_b32_e32 v185, 0xffff0000, v129
	v_lshlrev_b32_e32 v186, 16, v161
	v_and_b32_e32 v187, 0xffff0000, v161
	v_pk_fma_f32 v[246:247], v[246:247], v[184:185], v[186:187]
	v_lshlrev_b32_e32 v184, 16, v130
	v_and_b32_e32 v185, 0xffff0000, v130
	v_lshlrev_b32_e32 v186, 16, v162
	v_and_b32_e32 v187, 0xffff0000, v162
	v_pk_fma_f32 v[220:221], v[220:221], v[184:185], v[186:187]
	v_lshlrev_b32_e32 v184, 16, v131
	v_and_b32_e32 v185, 0xffff0000, v131
	v_lshlrev_b32_e32 v186, 16, v163
	v_and_b32_e32 v187, 0xffff0000, v163
	v_pk_fma_f32 v[222:223], v[222:223], v[184:185], v[186:187]
	v_cvt_pk_bf16_f32 v128, v244, v245
	v_cvt_pk_bf16_f32 v129, v246, v247
	v_cvt_pk_bf16_f32 v130, v220, v221
	v_cvt_pk_bf16_f32 v131, v222, v223
	global_store_dwordx4 v218, v[128:131], s[24:25]
	v_add_u32_e32 v219, 2, v212
	v_and_b32_e32 v219, 7, v219
	v_xor_b32_e32 v219, v213, v219
	v_add_u32_e32 v228, 2, v215
	v_lshlrev_b32_e32 v228, 10, v228
	v_lshl_add_u32 v228, v219, 4, v228
	v_xor_b32_e32 v229, 16, v228
	ds_read_b128 v[244:247], v228
	ds_read_b128 v[220:223], v229
	s_waitcnt vmcnt(13)
	s_waitcnt lgkmcnt(0)
	v_lshlrev_b32_e32 v184, 16, v132
	v_and_b32_e32 v185, 0xffff0000, v132
	v_lshlrev_b32_e32 v186, 16, v164
	v_and_b32_e32 v187, 0xffff0000, v164
	v_pk_fma_f32 v[244:245], v[244:245], v[184:185], v[186:187]
	v_lshlrev_b32_e32 v184, 16, v133
	v_and_b32_e32 v185, 0xffff0000, v133
	v_lshlrev_b32_e32 v186, 16, v165
	v_and_b32_e32 v187, 0xffff0000, v165
	v_pk_fma_f32 v[246:247], v[246:247], v[184:185], v[186:187]
	v_lshlrev_b32_e32 v184, 16, v134
	v_and_b32_e32 v185, 0xffff0000, v134
	v_lshlrev_b32_e32 v186, 16, v166
	v_and_b32_e32 v187, 0xffff0000, v166
	v_pk_fma_f32 v[220:221], v[220:221], v[184:185], v[186:187]
	v_lshlrev_b32_e32 v184, 16, v135
	v_and_b32_e32 v185, 0xffff0000, v135
	v_lshlrev_b32_e32 v186, 16, v167
	v_and_b32_e32 v187, 0xffff0000, v167
	v_pk_fma_f32 v[222:223], v[222:223], v[184:185], v[186:187]
	v_cvt_pk_bf16_f32 v132, v244, v245
	v_cvt_pk_bf16_f32 v133, v246, v247
	v_cvt_pk_bf16_f32 v134, v220, v221
	v_cvt_pk_bf16_f32 v135, v222, v223
	v_add_u32_e32 v219, 0x1000, v218
	global_store_dwordx4 v219, v[132:135], s[24:25]
	v_add_u32_e32 v219, 4, v212
	v_and_b32_e32 v219, 7, v219
	v_xor_b32_e32 v219, v213, v219
	v_add_u32_e32 v228, 4, v215
	v_lshlrev_b32_e32 v228, 10, v228
	v_lshl_add_u32 v228, v219, 4, v228
	v_xor_b32_e32 v229, 16, v228
	ds_read_b128 v[244:247], v228
	ds_read_b128 v[220:223], v229
	s_waitcnt vmcnt(12)
; #define EPI_FOR(u) \
;     _Pragma("unroll") for (int ai = 0; ai < 2; ++ai) _Pragma("unroll") for (int m = 0; m < 4; ++m) _Pragma("unroll") for (int bj = 0; bj < 2; ++bj)
; #define EPI_COL(u) (EPI_CB(u) + 8 * fq)
; DI u32x4 pack8(const float* v) { u32x4 w; w.x = pk2(v[0], v[1]); w.y = pk2(v[2], v[3]); w.z = pk2(v[4], v[5]); w.w = pk2(v[6], v[7]); return w; }
;     DI void operator()(const Acc& acc, const Unit& u, int wr, int wc, int fr, int fq) const {
;         EPI_FOR(u) {
;             const int row = EPI_ROW(u), col = EPI_COL(u); EPI_V(v);
;             const u32x4 gg = *(const u32x4*)(gate + (size_t)row * 3072 + gi * 1024 + col);
;             const float gf[8] = {bflo(gg.x), bfhi(gg.x), bflo(gg.y), bfhi(gg.y), bflo(gg.z), bfhi(gg.z), bflo(gg.w), bfhi(gg.w)};
;             bf16_t* mp = mrg + (size_t)row * 1024 + col;
;             if (accum) {
;                 const u32x4 oo = *(const u32x4*)mp;
;                 const float of[8] = {bflo(oo.x), bfhi(oo.x), bflo(oo.y), bfhi(oo.y), bflo(oo.z), bfhi(oo.z), bflo(oo.w), bfhi(oo.w)};
; #pragma unroll
;                 for (int j = 0; j < 8; ++j) v[j] = of[j] + gf[j] * v[j];
;             } else {
; #pragma unroll
;                 for (int j = 0; j < 8; ++j) v[j] = gf[j] * v[j];
;             }
;             *(u32x4*)mp = pack8(v);
;         }
	s_waitcnt lgkmcnt(0)
	v_lshlrev_b32_e32 v184, 16, v136
	v_and_b32_e32 v185, 0xffff0000, v136
	v_lshlrev_b32_e32 v186, 16, v168
	v_and_b32_e32 v187, 0xffff0000, v168
	v_pk_fma_f32 v[244:245], v[244:245], v[184:185], v[186:187]
	v_lshlrev_b32_e32 v184, 16, v137
	v_and_b32_e32 v185, 0xffff0000, v137
	v_lshlrev_b32_e32 v186, 16, v169
	v_and_b32_e32 v187, 0xffff0000, v169
	v_pk_fma_f32 v[246:247], v[246:247], v[184:185], v[186:187]
	v_lshlrev_b32_e32 v184, 16, v138
	v_and_b32_e32 v185, 0xffff0000, v138
	v_lshlrev_b32_e32 v186, 16, v170
	v_and_b32_e32 v187, 0xffff0000, v170
	v_pk_fma_f32 v[220:221], v[220:221], v[184:185], v[186:187]
	v_lshlrev_b32_e32 v184, 16, v139
	v_and_b32_e32 v185, 0xffff0000, v139
	v_lshlrev_b32_e32 v186, 16, v171
	v_and_b32_e32 v187, 0xffff0000, v171
	v_pk_fma_f32 v[222:223], v[222:223], v[184:185], v[186:187]
	v_cvt_pk_bf16_f32 v136, v244, v245
	v_cvt_pk_bf16_f32 v137, v246, v247
	v_cvt_pk_bf16_f32 v138, v220, v221
	v_cvt_pk_bf16_f32 v139, v222, v223
	v_add_u32_e32 v219, 0x2000, v218
	global_store_dwordx4 v219, v[136:139], s[24:25]
	v_add_u32_e32 v219, 6, v212
	v_and_b32_e32 v219, 7, v219
	v_xor_b32_e32 v219, v213, v219
	v_add_u32_e32 v228, 6, v215
	v_lshlrev_b32_e32 v228, 10, v228
	v_lshl_add_u32 v228, v219, 4, v228
	v_xor_b32_e32 v229, 16, v228
	ds_read_b128 v[244:247], v228
	ds_read_b128 v[220:223], v229
	s_waitcnt vmcnt(11)
	s_waitcnt lgkmcnt(0)
	v_lshlrev_b32_e32 v184, 16, v140
	v_and_b32_e32 v185, 0xffff0000, v140
	v_lshlrev_b32_e32 v186, 16, v172
	v_and_b32_e32 v187, 0xffff0000, v172
	v_pk_fma_f32 v[244:245], v[244:245], v[184:185], v[186:187]
	v_lshlrev_b32_e32 v184, 16, v141
	v_and_b32_e32 v185, 0xffff0000, v141
	v_lshlrev_b32_e32 v186, 16, v173
	v_and_b32_e32 v187, 0xffff0000, v173
	v_pk_fma_f32 v[246:247], v[246:247], v[184:185], v[186:187]
	v_lshlrev_b32_e32 v184, 16, v142
	v_and_b32_e32 v185, 0xffff0000, v142
	v_lshlrev_b32_e32 v186, 16, v174
	v_and_b32_e32 v187, 0xffff0000, v174
	v_pk_fma_f32 v[220:221], v[220:221], v[184:185], v[186:187]
	v_lshlrev_b32_e32 v184, 16, v143
	v_and_b32_e32 v185, 0xffff0000, v143
	v_lshlrev_b32_e32 v186, 16, v175
	v_and_b32_e32 v187, 0xffff0000, v175
	v_pk_fma_f32 v[222:223], v[222:223], v[184:185], v[186:187]
	v_cvt_pk_bf16_f32 v140, v244, v245
	v_cvt_pk_bf16_f32 v141, v246, v247
	v_cvt_pk_bf16_f32 v142, v220, v221
	v_cvt_pk_bf16_f32 v143, v222, v223
	v_add_u32_e32 v219, 0x3000, v218
	global_store_dwordx4 v219, v[140:143], s[24:25]
	v_add_u32_e32 v219, 8, v212
	v_and_b32_e32 v219, 7, v219
	v_xor_b32_e32 v219, v213, v219
	v_add_u32_e32 v228, 8, v215
	v_lshlrev_b32_e32 v228, 10, v228
	v_lshl_add_u32 v228, v219, 4, v228
	v_xor_b32_e32 v229, 16, v228
	ds_read_b128 v[244:247], v228
	ds_read_b128 v[220:223], v229
	s_waitcnt vmcnt(10)
	s_waitcnt lgkmcnt(0)
	v_lshlrev_b32_e32 v184, 16, v144
	v_and_b32_e32 v185, 0xffff0000, v144
	v_lshlrev_b32_e32 v186, 16, v176
	v_and_b32_e32 v187, 0xffff0000, v176
	v_pk_fma_f32 v[244:245], v[244:245], v[184:185], v[186:187]
	v_lshlrev_b32_e32 v184, 16, v145
	v_and_b32_e32 v185, 0xffff0000, v145
	v_lshlrev_b32_e32 v186, 16, v177
	v_and_b32_e32 v187, 0xffff0000, v177
	v_pk_fma_f32 v[246:247], v[246:247], v[184:185], v[186:187]
	v_lshlrev_b32_e32 v184, 16, v146
	v_and_b32_e32 v185, 0xffff0000, v146
	v_lshlrev_b32_e32 v186, 16, v178
	v_and_b32_e32 v187, 0xffff0000, v178
	v_pk_fma_f32 v[220:221], v[220:221], v[184:185], v[186:187]
	v_lshlrev_b32_e32 v184, 16, v147
	v_and_b32_e32 v185, 0xffff0000, v147
	v_lshlrev_b32_e32 v186, 16, v179
	v_and_b32_e32 v187, 0xffff0000, v179
	v_pk_fma_f32 v[222:223], v[222:223], v[184:185], v[186:187]
	v_cvt_pk_bf16_f32 v144, v244, v245
	v_cvt_pk_bf16_f32 v145, v246, v247
	v_cvt_pk_bf16_f32 v146, v220, v221
	v_cvt_pk_bf16_f32 v147, v222, v223
	v_add_u32_e32 v219, 0x4000, v218
	global_store_dwordx4 v219, v[144:147], s[24:25]
	v_add_u32_e32 v219, 10, v212
	v_and_b32_e32 v219, 7, v219
	v_xor_b32_e32 v219, v213, v219
	v_add_u32_e32 v228, 10, v215
	v_lshlrev_b32_e32 v228, 10, v228
	v_lshl_add_u32 v228, v219, 4, v228
	v_xor_b32_e32 v229, 16, v228
	ds_read_b128 v[244:247], v228
	ds_read_b128 v[220:223], v229
	s_waitcnt vmcnt(9)
	s_waitcnt lgkmcnt(0)
	v_lshlrev_b32_e32 v184, 16, v148
	v_and_b32_e32 v185, 0xffff0000, v148
	v_lshlrev_b32_e32 v186, 16, v180
	v_and_b32_e32 v187, 0xffff0000, v180
	v_pk_fma_f32 v[244:245], v[244:245], v[184:185], v[186:187]
	v_lshlrev_b32_e32 v184, 16, v149
	v_and_b32_e32 v185, 0xffff0000, v149
	v_lshlrev_b32_e32 v186, 16, v181
	v_and_b32_e32 v187, 0xffff0000, v181
	v_pk_fma_f32 v[246:247], v[246:247], v[184:185], v[186:187]
	v_lshlrev_b32_e32 v184, 16, v150
	v_and_b32_e32 v185, 0xffff0000, v150
	v_lshlrev_b32_e32 v186, 16, v182
	v_and_b32_e32 v187, 0xffff0000, v182
	v_pk_fma_f32 v[220:221], v[220:221], v[184:185], v[186:187]
	v_lshlrev_b32_e32 v184, 16, v151
	v_and_b32_e32 v185, 0xffff0000, v151
	v_lshlrev_b32_e32 v186, 16, v183
	v_and_b32_e32 v187, 0xffff0000, v183
	v_pk_fma_f32 v[222:223], v[222:223], v[184:185], v[186:187]
	v_cvt_pk_bf16_f32 v148, v244, v245
	v_cvt_pk_bf16_f32 v149, v246, v247
	v_cvt_pk_bf16_f32 v150, v220, v221
	v_cvt_pk_bf16_f32 v151, v222, v223
	v_add_u32_e32 v219, 0x5000, v218
	global_store_dwordx4 v219, v[148:151], s[24:25]
	v_add_u32_e32 v219, 12, v212
	v_and_b32_e32 v219, 7, v219
	v_xor_b32_e32 v219, v213, v219
	v_add_u32_e32 v228, 12, v215
	v_lshlrev_b32_e32 v228, 10, v228
	v_lshl_add_u32 v228, v219, 4, v228
	v_xor_b32_e32 v229, 16, v228
	ds_read_b128 v[244:247], v228
	ds_read_b128 v[220:223], v229
	s_waitcnt vmcnt(8)
	s_waitcnt lgkmcnt(0)
; #define EPI_FOR(u) \
;     _Pragma("unroll") for (int ai = 0; ai < 2; ++ai) _Pragma("unroll") for (int m = 0; m < 4; ++m) _Pragma("unroll") for (int bj = 0; bj < 2; ++bj)
; #define EPI_COL(u) (EPI_CB(u) + 8 * fq)
; DI u32x4 pack8(const float* v) { u32x4 w; w.x = pk2(v[0], v[1]); w.y = pk2(v[2], v[3]); w.z = pk2(v[4], v[5]); w.w = pk2(v[6], v[7]); return w; }
;     DI void operator()(const Acc& acc, const Unit& u, int wr, int wc, int fr, int fq) const {
;         EPI_FOR(u) {
;             const int row = EPI_ROW(u), col = EPI_COL(u); EPI_V(v);
;             const u32x4 gg = *(const u32x4*)(gate + (size_t)row * 3072 + gi * 1024 + col);
;             const float gf[8] = {bflo(gg.x), bfhi(gg.x), bflo(gg.y), bfhi(gg.y), bflo(gg.z), bfhi(gg.z), bflo(gg.w), bfhi(gg.w)};
;             bf16_t* mp = mrg + (size_t)row * 1024 + col;
;             if (accum) {
;                 const u32x4 oo = *(const u32x4*)mp;
;                 const float of[8] = {bflo(oo.x), bfhi(oo.x), bflo(oo.y), bfhi(oo.y), bflo(oo.z), bfhi(oo.z), bflo(oo.w), bfhi(oo.w)};
; #pragma unroll
;                 for (int j = 0; j < 8; ++j) v[j] = of[j] + gf[j] * v[j];
;             } else {
; #pragma unroll
;                 for (int j = 0; j < 8; ++j) v[j] = gf[j] * v[j];
;             }
;             *(u32x4*)mp = pack8(v);
;         }
	v_lshlrev_b32_e32 v184, 16, v152
	v_and_b32_e32 v185, 0xffff0000, v152
	v_lshlrev_b32_e32 v186, 16, v224
	v_and_b32_e32 v187, 0xffff0000, v224
	v_pk_fma_f32 v[244:245], v[244:245], v[184:185], v[186:187]
	v_lshlrev_b32_e32 v184, 16, v153
	v_and_b32_e32 v185, 0xffff0000, v153
	v_lshlrev_b32_e32 v186, 16, v225
	v_and_b32_e32 v187, 0xffff0000, v225
	v_pk_fma_f32 v[246:247], v[246:247], v[184:185], v[186:187]
	v_lshlrev_b32_e32 v184, 16, v154
	v_and_b32_e32 v185, 0xffff0000, v154
	v_lshlrev_b32_e32 v186, 16, v226
	v_and_b32_e32 v187, 0xffff0000, v226
	v_pk_fma_f32 v[220:221], v[220:221], v[184:185], v[186:187]
	v_lshlrev_b32_e32 v184, 16, v155
	v_and_b32_e32 v185, 0xffff0000, v155
	v_lshlrev_b32_e32 v186, 16, v227
	v_and_b32_e32 v187, 0xffff0000, v227
	v_pk_fma_f32 v[222:223], v[222:223], v[184:185], v[186:187]
	v_cvt_pk_bf16_f32 v152, v244, v245
	v_cvt_pk_bf16_f32 v153, v246, v247
	v_cvt_pk_bf16_f32 v154, v220, v221
	v_cvt_pk_bf16_f32 v155, v222, v223
	v_add_u32_e32 v219, 0x6000, v218
	global_store_dwordx4 v219, v[152:155], s[24:25]
	v_add_u32_e32 v219, 14, v212
	v_and_b32_e32 v219, 7, v219
	v_xor_b32_e32 v219, v213, v219
	v_add_u32_e32 v228, 14, v215
	v_lshlrev_b32_e32 v228, 10, v228
	v_lshl_add_u32 v228, v219, 4, v228
	v_xor_b32_e32 v229, 16, v228
	ds_read_b128 v[244:247], v228
	ds_read_b128 v[220:223], v229
	s_waitcnt vmcnt(7)
	s_waitcnt lgkmcnt(0)
	v_lshlrev_b32_e32 v184, 16, v156
	v_and_b32_e32 v185, 0xffff0000, v156
	v_lshlrev_b32_e32 v186, 16, v240
	v_and_b32_e32 v187, 0xffff0000, v240
	v_pk_fma_f32 v[244:245], v[244:245], v[184:185], v[186:187]
	v_lshlrev_b32_e32 v184, 16, v157
	v_and_b32_e32 v185, 0xffff0000, v157
	v_lshlrev_b32_e32 v186, 16, v241
	v_and_b32_e32 v187, 0xffff0000, v241
	v_pk_fma_f32 v[246:247], v[246:247], v[184:185], v[186:187]
	v_lshlrev_b32_e32 v184, 16, v158
	v_and_b32_e32 v185, 0xffff0000, v158
	v_lshlrev_b32_e32 v186, 16, v242
	v_and_b32_e32 v187, 0xffff0000, v242
	v_pk_fma_f32 v[220:221], v[220:221], v[184:185], v[186:187]
	v_lshlrev_b32_e32 v184, 16, v159
	v_and_b32_e32 v185, 0xffff0000, v159
	v_lshlrev_b32_e32 v186, 16, v243
	v_and_b32_e32 v187, 0xffff0000, v243
	v_pk_fma_f32 v[222:223], v[222:223], v[184:185], v[186:187]
	v_cvt_pk_bf16_f32 v156, v244, v245
	v_cvt_pk_bf16_f32 v157, v246, v247
	v_cvt_pk_bf16_f32 v158, v220, v221
	v_cvt_pk_bf16_f32 v159, v222, v223
	v_add_u32_e32 v219, 0x7000, v218
	global_store_dwordx4 v219, v[156:159], s[24:25]
	s_barrier
	ds_write_b128 v210, v[60:63]
	ds_write_b128 v211, v[56:59]
	ds_write_b128 v210, v[52:55] offset:512
	ds_write_b128 v211, v[48:51] offset:512
	ds_write_b128 v210, v[44:47] offset:16384
	ds_write_b128 v211, v[40:43] offset:16384
	ds_write_b128 v210, v[36:39] offset:16896
	ds_write_b128 v211, v[32:35] offset:16896
	ds_write_b128 v210, v[28:31] offset:32768
	ds_write_b128 v211, v[24:27] offset:32768
	ds_write_b128 v210, v[20:23] offset:33280
	ds_write_b128 v211, v[16:19] offset:33280
	ds_write_b128 v210, v[12:15] offset:49152
	ds_write_b128 v211, v[8:11] offset:49152
	ds_write_b128 v210, v[4:7] offset:49664
	ds_write_b128 v211, v[0:3] offset:49664
	s_waitcnt lgkmcnt(0)
	s_barrier
	v_add_u32_e32 v215, s7, v212
	s_add_i32 s8, s2, 128
	v_add_u32_e32 v216, s8, v215
	v_mul_u32_u24_e32 v217, 0x1800, v216
	v_add_u32_e32 v217, v217, v214
	v_add_u32_e32 v217, 0x800, v217
	v_lshl_add_u32 v218, v216, 11, v214
	global_load_dwordx4 v[128:131], v217, s[22:23]
	global_load_dwordx4 v[160:163], v218, s[24:25]
	v_add_u32_e32 v219, 0x3000, v217
	global_load_dwordx4 v[132:135], v219, s[22:23]
	v_add_u32_e32 v219, 0x1000, v218
	global_load_dwordx4 v[164:167], v219, s[24:25]
	v_add_u32_e32 v219, 0x6000, v217
	global_load_dwordx4 v[136:139], v219, s[22:23]
	v_add_u32_e32 v219, 0x2000, v218
	global_load_dwordx4 v[168:171], v219, s[24:25]
	v_add_u32_e32 v219, 0x9000, v217
	global_load_dwordx4 v[140:143], v219, s[22:23]
	v_add_u32_e32 v219, 0x3000, v218
	global_load_dwordx4 v[172:175], v219, s[24:25]
	v_add_u32_e32 v219, 0xc000, v217
	global_load_dwordx4 v[144:147], v219, s[22:23]
	v_add_u32_e32 v219, 0x4000, v218
	global_load_dwordx4 v[176:179], v219, s[24:25]
	v_add_u32_e32 v219, 0xf000, v217
	global_load_dwordx4 v[148:151], v219, s[22:23]
	v_add_u32_e32 v219, 0x5000, v218
	global_load_dwordx4 v[180:183], v219, s[24:25]
	v_add_u32_e32 v219, 0x12000, v217
	global_load_dwordx4 v[152:155], v219, s[22:23]
	v_add_u32_e32 v219, 0x6000, v218
	global_load_dwordx4 v[224:227], v219, s[24:25]
	v_add_u32_e32 v219, 0x15000, v217
	global_load_dwordx4 v[156:159], v219, s[22:23]
	v_add_u32_e32 v219, 0x7000, v218
	global_load_dwordx4 v[240:243], v219, s[24:25]
	v_add_u32_e32 v219, 0, v212
	v_and_b32_e32 v219, 7, v219
	v_xor_b32_e32 v219, v213, v219
	v_add_u32_e32 v228, 0, v215
	v_lshlrev_b32_e32 v228, 10, v228
	v_lshl_add_u32 v228, v219, 4, v228
	v_xor_b32_e32 v229, 16, v228
	ds_read_b128 v[244:247], v228
	ds_read_b128 v[220:223], v229
	s_waitcnt vmcnt(14)
	s_waitcnt lgkmcnt(0)
	v_lshlrev_b32_e32 v184, 16, v128
	v_and_b32_e32 v185, 0xffff0000, v128
	v_lshlrev_b32_e32 v186, 16, v160
	v_and_b32_e32 v187, 0xffff0000, v160
	v_pk_fma_f32 v[244:245], v[244:245], v[184:185], v[186:187]
	v_lshlrev_b32_e32 v184, 16, v129
	v_and_b32_e32 v185, 0xffff0000, v129
	v_lshlrev_b32_e32 v186, 16, v161
	v_and_b32_e32 v187, 0xffff0000, v161
	v_pk_fma_f32 v[246:247], v[246:247], v[184:185], v[186:187]
	v_lshlrev_b32_e32 v184, 16, v130
	v_and_b32_e32 v185, 0xffff0000, v130
	v_lshlrev_b32_e32 v186, 16, v162
	v_and_b32_e32 v187, 0xffff0000, v162
	v_pk_fma_f32 v[220:221], v[220:221], v[184:185], v[186:187]
	v_lshlrev_b32_e32 v184, 16, v131
	v_and_b32_e32 v185, 0xffff0000, v131
	v_lshlrev_b32_e32 v186, 16, v163
	v_and_b32_e32 v187, 0xffff0000, v163
	v_pk_fma_f32 v[222:223], v[222:223], v[184:185], v[186:187]
	v_cvt_pk_bf16_f32 v128, v244, v245
	v_cvt_pk_bf16_f32 v129, v246, v247
	v_cvt_pk_bf16_f32 v130, v220, v221
	v_cvt_pk_bf16_f32 v131, v222, v223
	global_store_dwordx4 v218, v[128:131], s[24:25]
	v_add_u32_e32 v219, 2, v212
	v_and_b32_e32 v219, 7, v219
	v_xor_b32_e32 v219, v213, v219
	v_add_u32_e32 v228, 2, v215
	v_lshlrev_b32_e32 v228, 10, v228
	v_lshl_add_u32 v228, v219, 4, v228
	v_xor_b32_e32 v229, 16, v228
	ds_read_b128 v[244:247], v228
	ds_read_b128 v[220:223], v229
	s_waitcnt vmcnt(13)
; #define EPI_FOR(u) \
;     _Pragma("unroll") for (int ai = 0; ai < 2; ++ai) _Pragma("unroll") for (int m = 0; m < 4; ++m) _Pragma("unroll") for (int bj = 0; bj < 2; ++bj)
; #define EPI_COL(u) (EPI_CB(u) + 8 * fq)
; DI u32x4 pack8(const float* v) { u32x4 w; w.x = pk2(v[0], v[1]); w.y = pk2(v[2], v[3]); w.z = pk2(v[4], v[5]); w.w = pk2(v[6], v[7]); return w; }
;     DI void operator()(const Acc& acc, const Unit& u, int wr, int wc, int fr, int fq) const {
;         EPI_FOR(u) {
;             const int row = EPI_ROW(u), col = EPI_COL(u); EPI_V(v);
;             const u32x4 gg = *(const u32x4*)(gate + (size_t)row * 3072 + gi * 1024 + col);
;             const float gf[8] = {bflo(gg.x), bfhi(gg.x), bflo(gg.y), bfhi(gg.y), bflo(gg.z), bfhi(gg.z), bflo(gg.w), bfhi(gg.w)};
;             bf16_t* mp = mrg + (size_t)row * 1024 + col;
;             if (accum) {
;                 const u32x4 oo = *(const u32x4*)mp;
;                 const float of[8] = {bflo(oo.x), bfhi(oo.x), bflo(oo.y), bfhi(oo.y), bflo(oo.z), bfhi(oo.z), bflo(oo.w), bfhi(oo.w)};
; #pragma unroll
;                 for (int j = 0; j < 8; ++j) v[j] = of[j] + gf[j] * v[j];
;             } else {
; #pragma unroll
;                 for (int j = 0; j < 8; ++j) v[j] = gf[j] * v[j];
;             }
;             *(u32x4*)mp = pack8(v);
;         }
	s_waitcnt lgkmcnt(0)
	v_lshlrev_b32_e32 v184, 16, v132
	v_and_b32_e32 v185, 0xffff0000, v132
	v_lshlrev_b32_e32 v186, 16, v164
	v_and_b32_e32 v187, 0xffff0000, v164
	v_pk_fma_f32 v[244:245], v[244:245], v[184:185], v[186:187]
	v_lshlrev_b32_e32 v184, 16, v133
	v_and_b32_e32 v185, 0xffff0000, v133
	v_lshlrev_b32_e32 v186, 16, v165
	v_and_b32_e32 v187, 0xffff0000, v165
	v_pk_fma_f32 v[246:247], v[246:247], v[184:185], v[186:187]
	v_lshlrev_b32_e32 v184, 16, v134
	v_and_b32_e32 v185, 0xffff0000, v134
	v_lshlrev_b32_e32 v186, 16, v166
	v_and_b32_e32 v187, 0xffff0000, v166
	v_pk_fma_f32 v[220:221], v[220:221], v[184:185], v[186:187]
	v_lshlrev_b32_e32 v184, 16, v135
	v_and_b32_e32 v185, 0xffff0000, v135
	v_lshlrev_b32_e32 v186, 16, v167
	v_and_b32_e32 v187, 0xffff0000, v167
	v_pk_fma_f32 v[222:223], v[222:223], v[184:185], v[186:187]
	v_cvt_pk_bf16_f32 v132, v244, v245
	v_cvt_pk_bf16_f32 v133, v246, v247
	v_cvt_pk_bf16_f32 v134, v220, v221
	v_cvt_pk_bf16_f32 v135, v222, v223
	v_add_u32_e32 v219, 0x1000, v218
	global_store_dwordx4 v219, v[132:135], s[24:25]
	v_add_u32_e32 v219, 4, v212
	v_and_b32_e32 v219, 7, v219
	v_xor_b32_e32 v219, v213, v219
	v_add_u32_e32 v228, 4, v215
	v_lshlrev_b32_e32 v228, 10, v228
	v_lshl_add_u32 v228, v219, 4, v228
	v_xor_b32_e32 v229, 16, v228
	ds_read_b128 v[244:247], v228
	ds_read_b128 v[220:223], v229
	s_waitcnt vmcnt(12)
	s_waitcnt lgkmcnt(0)
	v_lshlrev_b32_e32 v184, 16, v136
	v_and_b32_e32 v185, 0xffff0000, v136
	v_lshlrev_b32_e32 v186, 16, v168
	v_and_b32_e32 v187, 0xffff0000, v168
	v_pk_fma_f32 v[244:245], v[244:245], v[184:185], v[186:187]
	v_lshlrev_b32_e32 v184, 16, v137
	v_and_b32_e32 v185, 0xffff0000, v137
	v_lshlrev_b32_e32 v186, 16, v169
	v_and_b32_e32 v187, 0xffff0000, v169
	v_pk_fma_f32 v[246:247], v[246:247], v[184:185], v[186:187]
	v_lshlrev_b32_e32 v184, 16, v138
	v_and_b32_e32 v185, 0xffff0000, v138
	v_lshlrev_b32_e32 v186, 16, v170
	v_and_b32_e32 v187, 0xffff0000, v170
	v_pk_fma_f32 v[220:221], v[220:221], v[184:185], v[186:187]
	v_lshlrev_b32_e32 v184, 16, v139
	v_and_b32_e32 v185, 0xffff0000, v139
	v_lshlrev_b32_e32 v186, 16, v171
	v_and_b32_e32 v187, 0xffff0000, v171
	v_pk_fma_f32 v[222:223], v[222:223], v[184:185], v[186:187]
	v_cvt_pk_bf16_f32 v136, v244, v245
	v_cvt_pk_bf16_f32 v137, v246, v247
	v_cvt_pk_bf16_f32 v138, v220, v221
	v_cvt_pk_bf16_f32 v139, v222, v223
	v_add_u32_e32 v219, 0x2000, v218
	global_store_dwordx4 v219, v[136:139], s[24:25]
	v_add_u32_e32 v219, 6, v212
	v_and_b32_e32 v219, 7, v219
	v_xor_b32_e32 v219, v213, v219
	v_add_u32_e32 v228, 6, v215
	v_lshlrev_b32_e32 v228, 10, v228
	v_lshl_add_u32 v228, v219, 4, v228
	v_xor_b32_e32 v229, 16, v228
	ds_read_b128 v[244:247], v228
	ds_read_b128 v[220:223], v229
	s_waitcnt vmcnt(11)
	s_waitcnt lgkmcnt(0)
	v_lshlrev_b32_e32 v184, 16, v140
	v_and_b32_e32 v185, 0xffff0000, v140
	v_lshlrev_b32_e32 v186, 16, v172
	v_and_b32_e32 v187, 0xffff0000, v172
	v_pk_fma_f32 v[244:245], v[244:245], v[184:185], v[186:187]
	v_lshlrev_b32_e32 v184, 16, v141
	v_and_b32_e32 v185, 0xffff0000, v141
	v_lshlrev_b32_e32 v186, 16, v173
	v_and_b32_e32 v187, 0xffff0000, v173
	v_pk_fma_f32 v[246:247], v[246:247], v[184:185], v[186:187]
	v_lshlrev_b32_e32 v184, 16, v142
	v_and_b32_e32 v185, 0xffff0000, v142
	v_lshlrev_b32_e32 v186, 16, v174
	v_and_b32_e32 v187, 0xffff0000, v174
	v_pk_fma_f32 v[220:221], v[220:221], v[184:185], v[186:187]
	v_lshlrev_b32_e32 v184, 16, v143
	v_and_b32_e32 v185, 0xffff0000, v143
	v_lshlrev_b32_e32 v186, 16, v175
	v_and_b32_e32 v187, 0xffff0000, v175
	v_pk_fma_f32 v[222:223], v[222:223], v[184:185], v[186:187]
	v_cvt_pk_bf16_f32 v140, v244, v245
	v_cvt_pk_bf16_f32 v141, v246, v247
	v_cvt_pk_bf16_f32 v142, v220, v221
	v_cvt_pk_bf16_f32 v143, v222, v223
	v_add_u32_e32 v219, 0x3000, v218
	global_store_dwordx4 v219, v[140:143], s[24:25]
	v_add_u32_e32 v219, 8, v212
	v_and_b32_e32 v219, 7, v219
	v_xor_b32_e32 v219, v213, v219
	v_add_u32_e32 v228, 8, v215
	v_lshlrev_b32_e32 v228, 10, v228
	v_lshl_add_u32 v228, v219, 4, v228
	v_xor_b32_e32 v229, 16, v228
	ds_read_b128 v[244:247], v228
	ds_read_b128 v[220:223], v229
	s_waitcnt vmcnt(10)
	s_waitcnt lgkmcnt(0)
; #define PG8_BAR __builtin_amdgcn_s_barrier()
; #define EPI_FOR(u) \
;     _Pragma("unroll") for (int ai = 0; ai < 2; ++ai) _Pragma("unroll") for (int m = 0; m < 4; ++m) _Pragma("unroll") for (int bj = 0; bj < 2; ++bj)
; #define EPI_COL(u) (EPI_CB(u) + 8 * fq)
; DI u32x4 pack8(const float* v) { u32x4 w; w.x = pk2(v[0], v[1]); w.y = pk2(v[2], v[3]); w.z = pk2(v[4], v[5]); w.w = pk2(v[6], v[7]); return w; }
; template <class Epi>
; DI void gemm_phase(LAS unsigned char* lds, const Gemm g, const Sched& S, const Epi& E) {
;     ...
;         if (!has_next) break;
; #pragma unroll
;         for (int a = 0; a < 2; ++a)
; #pragma unroll
;             for (int b = 0; b < 2; ++b)
; #pragma unroll
;                 for (int m = 0; m < 4; ++m)
; #pragma unroll
;                     for (int n = 0; n < 2; ++n) acc[a][b][m][n] = (f32x4){0.f, 0.f, 0.f, 0.f};
;         cur = nxt; cA = nA; cB = nB; ++ui;
;         if (wr == 1) PG8_BAR;
;     DI void operator()(const Acc& acc, const Unit& u, int wr, int wc, int fr, int fq) const {
;         EPI_FOR(u) {
;             const int row = EPI_ROW(u), col = EPI_COL(u); EPI_V(v);
;             const u32x4 gg = *(const u32x4*)(gate + (size_t)row * 3072 + gi * 1024 + col);
;             const float gf[8] = {bflo(gg.x), bfhi(gg.x), bflo(gg.y), bfhi(gg.y), bflo(gg.z), bfhi(gg.z), bflo(gg.w), bfhi(gg.w)};
;             bf16_t* mp = mrg + (size_t)row * 1024 + col;
;             if (accum) {
;                 const u32x4 oo = *(const u32x4*)mp;
;                 const float of[8] = {bflo(oo.x), bfhi(oo.x), bflo(oo.y), bfhi(oo.y), bflo(oo.z), bfhi(oo.z), bflo(oo.w), bfhi(oo.w)};
; #pragma unroll
;                 for (int j = 0; j < 8; ++j) v[j] = of[j] + gf[j] * v[j];
;             } else {
; #pragma unroll
;                 for (int j = 0; j < 8; ++j) v[j] = gf[j] * v[j];
;             }
;             *(u32x4*)mp = pack8(v);
;         }
	v_lshlrev_b32_e32 v184, 16, v144
	v_and_b32_e32 v185, 0xffff0000, v144
	v_lshlrev_b32_e32 v186, 16, v176
	v_and_b32_e32 v187, 0xffff0000, v176
	v_pk_fma_f32 v[244:245], v[244:245], v[184:185], v[186:187]
	v_lshlrev_b32_e32 v184, 16, v145
	v_and_b32_e32 v185, 0xffff0000, v145
	v_lshlrev_b32_e32 v186, 16, v177
	v_and_b32_e32 v187, 0xffff0000, v177
	v_pk_fma_f32 v[246:247], v[246:247], v[184:185], v[186:187]
	v_lshlrev_b32_e32 v184, 16, v146
	v_and_b32_e32 v185, 0xffff0000, v146
	v_lshlrev_b32_e32 v186, 16, v178
	v_and_b32_e32 v187, 0xffff0000, v178
	v_pk_fma_f32 v[220:221], v[220:221], v[184:185], v[186:187]
	v_lshlrev_b32_e32 v184, 16, v147
	v_and_b32_e32 v185, 0xffff0000, v147
	v_lshlrev_b32_e32 v186, 16, v179
	v_and_b32_e32 v187, 0xffff0000, v179
	v_pk_fma_f32 v[222:223], v[222:223], v[184:185], v[186:187]
	v_cvt_pk_bf16_f32 v144, v244, v245
	v_cvt_pk_bf16_f32 v145, v246, v247
	v_cvt_pk_bf16_f32 v146, v220, v221
	v_cvt_pk_bf16_f32 v147, v222, v223
	v_add_u32_e32 v219, 0x4000, v218
	global_store_dwordx4 v219, v[144:147], s[24:25]
	v_add_u32_e32 v219, 10, v212
	v_and_b32_e32 v219, 7, v219
	v_xor_b32_e32 v219, v213, v219
	v_add_u32_e32 v228, 10, v215
	v_lshlrev_b32_e32 v228, 10, v228
	v_lshl_add_u32 v228, v219, 4, v228
	v_xor_b32_e32 v229, 16, v228
	ds_read_b128 v[244:247], v228
	ds_read_b128 v[220:223], v229
	s_waitcnt vmcnt(9)
	s_waitcnt lgkmcnt(0)
	v_lshlrev_b32_e32 v184, 16, v148
	v_and_b32_e32 v185, 0xffff0000, v148
	v_lshlrev_b32_e32 v186, 16, v180
	v_and_b32_e32 v187, 0xffff0000, v180
	v_pk_fma_f32 v[244:245], v[244:245], v[184:185], v[186:187]
	v_lshlrev_b32_e32 v184, 16, v149
	v_and_b32_e32 v185, 0xffff0000, v149
	v_lshlrev_b32_e32 v186, 16, v181
	v_and_b32_e32 v187, 0xffff0000, v181
	v_pk_fma_f32 v[246:247], v[246:247], v[184:185], v[186:187]
	v_lshlrev_b32_e32 v184, 16, v150
	v_and_b32_e32 v185, 0xffff0000, v150
	v_lshlrev_b32_e32 v186, 16, v182
	v_and_b32_e32 v187, 0xffff0000, v182
	v_pk_fma_f32 v[220:221], v[220:221], v[184:185], v[186:187]
	v_lshlrev_b32_e32 v184, 16, v151
	v_and_b32_e32 v185, 0xffff0000, v151
	v_lshlrev_b32_e32 v186, 16, v183
	v_and_b32_e32 v187, 0xffff0000, v183
	v_pk_fma_f32 v[222:223], v[222:223], v[184:185], v[186:187]
	v_cvt_pk_bf16_f32 v148, v244, v245
	v_cvt_pk_bf16_f32 v149, v246, v247
	v_cvt_pk_bf16_f32 v150, v220, v221
	v_cvt_pk_bf16_f32 v151, v222, v223
	v_add_u32_e32 v219, 0x5000, v218
	global_store_dwordx4 v219, v[148:151], s[24:25]
	v_add_u32_e32 v219, 12, v212
	v_and_b32_e32 v219, 7, v219
	v_xor_b32_e32 v219, v213, v219
	v_add_u32_e32 v228, 12, v215
	v_lshlrev_b32_e32 v228, 10, v228
	v_lshl_add_u32 v228, v219, 4, v228
	v_xor_b32_e32 v229, 16, v228
	ds_read_b128 v[244:247], v228
	ds_read_b128 v[220:223], v229
	s_waitcnt vmcnt(8)
	s_waitcnt lgkmcnt(0)
	v_lshlrev_b32_e32 v184, 16, v152
	v_and_b32_e32 v185, 0xffff0000, v152
	v_lshlrev_b32_e32 v186, 16, v224
	v_and_b32_e32 v187, 0xffff0000, v224
	v_pk_fma_f32 v[244:245], v[244:245], v[184:185], v[186:187]
	v_lshlrev_b32_e32 v184, 16, v153
	v_and_b32_e32 v185, 0xffff0000, v153
	v_lshlrev_b32_e32 v186, 16, v225
	v_and_b32_e32 v187, 0xffff0000, v225
	v_pk_fma_f32 v[246:247], v[246:247], v[184:185], v[186:187]
	v_lshlrev_b32_e32 v184, 16, v154
	v_and_b32_e32 v185, 0xffff0000, v154
	v_lshlrev_b32_e32 v186, 16, v226
	v_and_b32_e32 v187, 0xffff0000, v226
	v_pk_fma_f32 v[220:221], v[220:221], v[184:185], v[186:187]
	v_lshlrev_b32_e32 v184, 16, v155
	v_and_b32_e32 v185, 0xffff0000, v155
	v_lshlrev_b32_e32 v186, 16, v227
	v_and_b32_e32 v187, 0xffff0000, v227
	v_pk_fma_f32 v[222:223], v[222:223], v[184:185], v[186:187]
	v_cvt_pk_bf16_f32 v152, v244, v245
	v_cvt_pk_bf16_f32 v153, v246, v247
	v_cvt_pk_bf16_f32 v154, v220, v221
	v_cvt_pk_bf16_f32 v155, v222, v223
	v_add_u32_e32 v219, 0x6000, v218
	global_store_dwordx4 v219, v[152:155], s[24:25]
	v_add_u32_e32 v219, 14, v212
	v_and_b32_e32 v219, 7, v219
	v_xor_b32_e32 v219, v213, v219
	v_add_u32_e32 v228, 14, v215
	v_lshlrev_b32_e32 v228, 10, v228
	v_lshl_add_u32 v228, v219, 4, v228
	v_xor_b32_e32 v229, 16, v228
	ds_read_b128 v[244:247], v228
	ds_read_b128 v[220:223], v229
	s_waitcnt vmcnt(7)
	s_waitcnt lgkmcnt(0)
	v_lshlrev_b32_e32 v184, 16, v156
	v_and_b32_e32 v185, 0xffff0000, v156
	v_lshlrev_b32_e32 v186, 16, v240
	v_and_b32_e32 v187, 0xffff0000, v240
	v_pk_fma_f32 v[244:245], v[244:245], v[184:185], v[186:187]
	v_lshlrev_b32_e32 v184, 16, v157
	v_and_b32_e32 v185, 0xffff0000, v157
	v_lshlrev_b32_e32 v186, 16, v241
	v_and_b32_e32 v187, 0xffff0000, v241
	v_pk_fma_f32 v[246:247], v[246:247], v[184:185], v[186:187]
	v_lshlrev_b32_e32 v184, 16, v158
	v_and_b32_e32 v185, 0xffff0000, v158
	v_lshlrev_b32_e32 v186, 16, v242
	v_and_b32_e32 v187, 0xffff0000, v242
	v_pk_fma_f32 v[220:221], v[220:221], v[184:185], v[186:187]
	v_lshlrev_b32_e32 v184, 16, v159
	v_and_b32_e32 v185, 0xffff0000, v159
	v_lshlrev_b32_e32 v186, 16, v243
	v_and_b32_e32 v187, 0xffff0000, v243
	v_pk_fma_f32 v[222:223], v[222:223], v[184:185], v[186:187]
	v_cvt_pk_bf16_f32 v156, v244, v245
	v_cvt_pk_bf16_f32 v157, v246, v247
	v_cvt_pk_bf16_f32 v158, v220, v221
	v_cvt_pk_bf16_f32 v159, v222, v223
	v_add_u32_e32 v219, 0x7000, v218
	global_store_dwordx4 v219, v[156:159], s[24:25]
	s_mov_b64 s[6:7], -1
	s_and_b64 vcc, exec, s[14:15]
	s_cbranch_vccnz .LBB0_1233
	s_andn2_b64 vcc, exec, s[20:21]
	s_cbranch_vccnz .LBB0_1232
	s_barrier
	s_branch .LBB0_1232
